# BO3 + loop-edge rotation in sliver loops + mid-block priority window of two MFMAs
# speedup vs baseline: 1.0015x; 1.0002x over previous
; #define PG8_STAGE(bufoff, gbase, voff) do { _Pragma("unroll") for (int _i = 0; _i < 2; ++_i) \
;         __builtin_amdgcn_global_load_lds((const unsigned*)((const char*)(gbase) + (size_t)_i * qstep + (voff)[0]), (PG8_LAS unsigned*)(lds + (bufoff) + ldsw + _i * 8192), 16, 0, 0); } while (0)
; #define PG8_LDA(dst, b, h) do { _Pragma("unroll") for (int m = 0; m < 4; ++m) _Pragma("unroll") for (int k = 0; k < 2; ++k) dst[m][k] = *(const PG8_LAS bf16x8*)(lds + PG8_SA(b, h) + aoff + m * 2048 + k * 1024); } while (0)
; #define PG8_LDB(dst, b, h) do { _Pragma("unroll") for (int n = 0; n < 2; ++n) _Pragma("unroll") for (int k = 0; k < 2; ++k) dst[n][k] = *(const PG8_LAS bf16x8*)(lds + PG8_SB(b, h) + boff + n * 2048 + k * 1024); } while (0)
; #define PG8_MMA(ai, bj, At, Bt) do { __builtin_amdgcn_s_setprio(1); _Pragma("unroll") for (int m = 0; m < 4; ++m) _Pragma("unroll") for (int n = 0; n < 2; ++n) _Pragma("unroll") for (int k = 0; k < 2; ++k) \
;         acc[ai][bj][m][n] = __builtin_amdgcn_mfma_f32_16x16x32_bf16(Bt[n][k], At[m][k], acc[ai][bj][m][n], 0, 0, 0); __builtin_amdgcn_s_setprio(0); } while (0)
; #define PG8_WAIT_V89() do { if constexpr (SLIVER) PG8_WAIT_V(9); else PG8_WAIT_V(8); } while (0)
; #define PG8_WAIT_L(n) asm volatile("s_waitcnt lgkmcnt(" #n ")" ::: "memory")
; #define PG8_BAR __builtin_amdgcn_s_barrier()
; #define PG8_SCHED __builtin_amdgcn_sched_barrier(0)
; template <class Epi, class Sched, bool ALIGN_EPI = false, bool SP2 = false, bool SLIVER = false>
; __device__ __forceinline__ void gemm_phase(PG8_LAS unsigned char* lds, const Gemm g, const Sched& S, const Epi& E) {
;     ...
;             const bool last = (t == nt - 2);
;             const char* a1 = cA + (size_t)(t + 1) * kstep;
;             const char* a2 = last ? nA : cA + (size_t)(t + 2) * kstep; const char* b2 = last ? nB : cB + (size_t)(t + 2) * kstep;
;             const char* a3 = a2 + kstep; const char* b3 = b2 + kstep;
;             const char* s1 = cS + (size_t)(t + 1) * kstep; const char* s2 = last ? nS : cS + (size_t)(t + 2) * kstep;
;             if (last && has_next) S.a_ready(nxt);
;             if constexpr (SP2) {
;             PG8_LDB(B0, 0, 0); PG8_LDB(B1, 0, 1); PG8_SCHED; PG8_LDA(At, 0, 0); PG8_STAGE(PG8_SA(1, 1), a1 + hstep, voffA); PG8_STAGE_S(1, s1);
;             PG8_WAIT_V89(); PG8_WAIT_L(0); PG8_BAR; PG8_MMA(0, 0, At, B0); PG8_MMA(0, 1, At, B1); PG8_BAR; PG8_SCHED;
.LBB0_498:
	s_cmp_eq_u32 s66, s80
	s_cselect_b64 s[86:87], -1, 0
	s_add_u32 s40, s16, s80
	s_addc_u32 s41, s17, s81
	s_add_u32 s68, s40, 0x100
	s_addc_u32 s69, s41, 0
	s_and_b64 s[40:41], s[86:87], exec
	s_cselect_b32 s41, s55, s69
	s_cselect_b32 s40, s54, s68
	s_add_u32 s76, s12, s80
	s_addc_u32 s77, s13, s81
	s_add_i32 s78, 0, 0x10000
	s_and_b64 s[68:69], s[86:87], exec
	v_add_u32_e32 v138, s78, v239
	s_cselect_b32 s69, s83, s77
	s_cselect_b32 s68, s82, s76
	s_add_i32 s76, 0, 0x14000
	ds_read_b128 v[146:149], v138
	ds_read_b128 v[150:153], v138 offset:1024
	ds_read_b128 v[154:157], v138 offset:2048
	ds_read_b128 v[158:161], v138 offset:3072
	v_add_u32_e32 v138, s76, v239
	ds_read_b128 v[166:169], v138
	ds_read_b128 v[170:173], v138 offset:1024
	ds_read_b128 v[174:177], v138 offset:2048
	ds_read_b128 v[162:165], v138 offset:3072
	v_lshl_add_u64 v[208:209], v[188:189], 0, s[80:81]
	v_lshl_add_u64 v[224:225], v[208:209], 0, s[34:35]
	s_add_i32 m0, s96, 0xc000
	s_mov_b64 s[88:89], 0x120080
	ds_read_b128 v[138:141], v242
	ds_read_b128 v[142:145], v242 offset:1024
	ds_read_b128 v[180:183], v242 offset:2048
	ds_read_b128 v[184:187], v242 offset:3072
	ds_read_b128 v[192:195], v242 offset:4096
	ds_read_b128 v[196:199], v242 offset:5120
	ds_read_b128 v[200:203], v242 offset:6144
	ds_read_b128 v[220:223], v242 offset:7168
	global_load_lds_dwordx4 v[224:225], off
	v_lshl_add_u64 v[208:209], v[208:209], 0, s[88:89]
	s_add_i32 m0, s96, 0xe000
	s_nop 0
	global_load_lds_dwordx4 v[208:209], off
	v_lshl_add_u64 v[208:209], v[190:191], 0, s[80:81]
	s_add_i32 m0, s94, 0x20800
	s_nop 0
	global_load_lds_dword v[208:209], off
	s_waitcnt vmcnt(9)
	s_waitcnt lgkmcnt(0)
	s_setprio 1
	s_barrier
	v_mfma_f32_16x16x32_bf16 v[134:137], v[146:149], v[138:141], v[134:137]
	v_mfma_f32_16x16x32_bf16 v[134:137], v[150:153], v[142:145], v[134:137]
	v_mfma_f32_16x16x32_bf16 v[130:133], v[158:161], v[142:145], v[130:133]
	v_mfma_f32_16x16x32_bf16 v[130:133], v[154:157], v[138:141], v[130:133]
	v_mfma_f32_16x16x32_bf16 v[122:125], v[154:157], v[180:183], v[122:125]
	v_mfma_f32_16x16x32_bf16 v[122:125], v[158:161], v[184:187], v[122:125]
	v_mfma_f32_16x16x32_bf16 v[126:129], v[150:153], v[184:187], v[126:129]
	v_mfma_f32_16x16x32_bf16 v[126:129], v[146:149], v[180:183], v[126:129]
	v_mfma_f32_16x16x32_bf16 v[118:121], v[146:149], v[192:195], v[118:121]
	v_mfma_f32_16x16x32_bf16 v[118:121], v[150:153], v[196:199], v[118:121]
	v_mfma_f32_16x16x32_bf16 v[114:117], v[158:161], v[196:199], v[114:117]
	v_mfma_f32_16x16x32_bf16 v[114:117], v[154:157], v[192:195], v[114:117]
	v_mfma_f32_16x16x32_bf16 v[106:109], v[154:157], v[200:203], v[106:109]
	v_mfma_f32_16x16x32_bf16 v[106:109], v[158:161], v[220:223], v[106:109]
	v_mfma_f32_16x16x32_bf16 v[110:113], v[150:153], v[220:223], v[110:113]
	v_mfma_f32_16x16x32_bf16 v[110:113], v[146:149], v[200:203], v[110:113]
	s_setprio 0
	v_mfma_f32_16x16x32_bf16 v[66:69], v[174:177], v[200:203], v[66:69]
	v_mfma_f32_16x16x32_bf16 v[66:69], v[162:165], v[220:223], v[66:69]
	s_setprio 1
	v_mfma_f32_16x16x32_bf16 v[98:101], v[162:165], v[142:145], v[98:101]
	v_mfma_f32_16x16x32_bf16 v[98:101], v[174:177], v[138:141], v[98:101]
	v_mfma_f32_16x16x32_bf16 v[102:105], v[166:169], v[138:141], v[102:105]
	v_mfma_f32_16x16x32_bf16 v[102:105], v[170:173], v[142:145], v[102:105]
	v_mfma_f32_16x16x32_bf16 v[90:93], v[170:173], v[184:187], v[90:93]
	v_mfma_f32_16x16x32_bf16 v[90:93], v[166:169], v[180:183], v[90:93]
	v_mfma_f32_16x16x32_bf16 v[86:89], v[174:177], v[180:183], v[86:89]
	v_mfma_f32_16x16x32_bf16 v[86:89], v[162:165], v[184:187], v[86:89]
	v_mfma_f32_16x16x32_bf16 v[74:77], v[162:165], v[196:199], v[74:77]
	v_mfma_f32_16x16x32_bf16 v[74:77], v[174:177], v[192:195], v[74:77]
	v_mfma_f32_16x16x32_bf16 v[78:81], v[166:169], v[192:195], v[78:81]
	v_mfma_f32_16x16x32_bf16 v[78:81], v[170:173], v[196:199], v[78:81]
	v_mfma_f32_16x16x32_bf16 v[70:73], v[170:173], v[220:223], v[70:73]
	v_mfma_f32_16x16x32_bf16 v[70:73], v[166:169], v[200:203], v[70:73]
	s_barrier
; #define PG8_SB(B) __builtin_amdgcn_rcpf(1.f + expneg(B))
; #define PG8_SB(B) __builtin_amdgcn_rcpf(1.f + expneg(B))
; #define PG8_STAGE(bufoff, gbase, voff) do { _Pragma("unroll") for (int _i = 0; _i < 2; ++_i) \
;         __builtin_amdgcn_global_load_lds((const unsigned*)((const char*)(gbase) + (size_t)_i * qstep + (voff)[0]), (PG8_LAS unsigned*)(lds + (bufoff) + ldsw + _i * 8192), 16, 0, 0); } while (0)
; #define PG8_LDA(dst, b, h) do { _Pragma("unroll") for (int m = 0; m < 4; ++m) _Pragma("unroll") for (int k = 0; k < 2; ++k) dst[m][k] = *(const PG8_LAS bf16x8*)(lds + PG8_SA(b, h) + aoff + m * 2048 + k * 1024); } while (0)
; #define PG8_MMA(ai, bj, At, Bt) do { __builtin_amdgcn_s_setprio(1); _Pragma("unroll") for (int m = 0; m < 4; ++m) _Pragma("unroll") for (int n = 0; n < 2; ++n) _Pragma("unroll") for (int k = 0; k < 2; ++k) \
;         acc[ai][bj][m][n] = __builtin_amdgcn_mfma_f32_16x16x32_bf16(Bt[n][k], At[m][k], acc[ai][bj][m][n], 0, 0, 0); __builtin_amdgcn_s_setprio(0); } while (0)
; #define PG8_WAIT_V89() do { if constexpr (SLIVER) PG8_WAIT_V(9); else PG8_WAIT_V(8); } while (0)
; #define PG8_LDS_S(b) do { if constexpr (SLIVER) { Sf[0] = *(const PG8_LAS bf16x8*)(lds + STAGE_BYTES + (b) * 2048 + soff0); Sf[1] = *(const PG8_LAS bf16x8*)(lds + STAGE_BYTES + (b) * 2048 + (soff0 ^ 64)); } } while (0)
; #define PG8_WAIT_L(n) asm volatile("s_waitcnt lgkmcnt(" #n ")" ::: "memory")
; #define PG8_BAR __builtin_amdgcn_s_barrier()
; #define PG8_SCHED __builtin_amdgcn_sched_barrier(0)
; template <class Epi, class Sched, bool ALIGN_EPI = false, bool SP2 = false, bool SLIVER = false>
; __device__ __forceinline__ void gemm_phase(PG8_LAS unsigned char* lds, const Gemm g, const Sched& S, const Epi& E) {
;     ...
;             PG8_LDA(At, 0, 1); PG8_LDS_S(0); PG8_STAGE(PG8_SB(0, 0), b2, voffB); PG8_STAGE(PG8_SB(0, 1), b2 + hstep, voffB); PG8_STAGE(PG8_SA(0, 0), a2, voffA);
;             PG8_WAIT_V89(); PG8_WAIT_L(0); PG8_BAR; PG8_MMA(1, 0, At, B0); PG8_MMA(1, 1, At, B1); PG8_MMA_S(); PG8_BAR; PG8_SCHED;
	s_setprio 0
	s_add_i32 s77, 0, 0x20000
	v_lshl_add_u64 v[192:193], s[68:69], 0, v[212:213]
	s_add_i32 s68, s78, s95
	v_add_u32_e32 v178, s77, v240
	v_add_u32_e32 v184, s77, v241
	s_mov_b32 m0, s68
	s_mov_b64 s[88:89], 0x60000
	ds_read_b128 v[138:141], v242 offset:16384
	ds_read_b128 v[142:145], v242 offset:17408
	ds_read_b128 v[196:199], v242 offset:18432
	ds_read_b128 v[200:203], v242 offset:19456
	ds_read_b128 v[220:223], v242 offset:20480
	ds_read_b128 v[224:227], v242 offset:21504
	ds_read_b128 v[228:231], v242 offset:22528
	ds_read_b128 v[232:235], v242 offset:23552
	ds_read_b128 v[180:183], v178
	ds_read_b128 v[184:187], v184
	global_load_lds_dwordx4 v[192:193], off
	v_lshl_add_u64 v[194:195], v[192:193], 0, s[88:89]
	s_add_i32 m0, s68, 0x2000
	s_add_i32 s68, s76, s95
	global_load_lds_dwordx4 v[194:195], off
	v_lshl_add_u64 v[194:195], v[192:193], 0, s[24:25]
	s_mov_b32 m0, s68
	s_nop 0
	global_load_lds_dwordx4 v[194:195], off
	v_lshl_add_u64 v[194:195], v[192:193], 0, s[14:15]
	s_add_i32 m0, s68, 0x2000
	s_nop 0
	global_load_lds_dwordx4 v[194:195], off
	v_lshl_add_u64 v[194:195], s[40:41], 0, v[210:211]
	s_mov_b32 m0, s96
	v_lshl_add_u64 v[208:209], v[194:195], 0, s[88:89]
	global_load_lds_dwordx4 v[194:195], off
	s_mov_b32 m0, s19
	s_nop 0
	global_load_lds_dwordx4 v[208:209], off
	s_waitcnt vmcnt(9)
	s_waitcnt lgkmcnt(0)
	s_setprio 1
	s_barrier
	v_mfma_f32_16x16x32_bf16 v[62:65], v[146:149], v[138:141], v[62:65]
	v_mfma_f32_16x16x32_bf16 v[62:65], v[150:153], v[142:145], v[62:65]
	v_mfma_f32_16x16x32_bf16 v[58:61], v[158:161], v[142:145], v[58:61]
	v_mfma_f32_16x16x32_bf16 v[58:61], v[154:157], v[138:141], v[58:61]
	v_mfma_f32_16x16x32_bf16 v[50:53], v[154:157], v[196:199], v[50:53]
	v_mfma_f32_16x16x32_bf16 v[50:53], v[158:161], v[200:203], v[50:53]
	v_mfma_f32_16x16x32_bf16 v[54:57], v[150:153], v[200:203], v[54:57]
	v_mfma_f32_16x16x32_bf16 v[54:57], v[146:149], v[196:199], v[54:57]
	v_mfma_f32_16x16x32_bf16 v[46:49], v[146:149], v[220:223], v[46:49]
	v_mfma_f32_16x16x32_bf16 v[46:49], v[150:153], v[224:227], v[46:49]
	v_mfma_f32_16x16x32_bf16 v[42:45], v[158:161], v[224:227], v[42:45]
	v_mfma_f32_16x16x32_bf16 v[42:45], v[154:157], v[220:223], v[42:45]
	v_mfma_f32_16x16x32_bf16 v[34:37], v[154:157], v[228:231], v[34:37]
	v_mfma_f32_16x16x32_bf16 v[34:37], v[158:161], v[232:235], v[34:37]
	v_mfma_f32_16x16x32_bf16 v[38:41], v[150:153], v[232:235], v[38:41]
	v_mfma_f32_16x16x32_bf16 v[38:41], v[146:149], v[228:231], v[38:41]
	s_setprio 0
	v_mfma_f32_16x16x32_bf16 v[2:5], v[174:177], v[228:231], v[2:5]
	v_mfma_f32_16x16x32_bf16 v[2:5], v[162:165], v[232:235], v[2:5]
	s_setprio 1
	v_mfma_f32_16x16x32_bf16 v[26:29], v[162:165], v[142:145], v[26:29]
	v_mfma_f32_16x16x32_bf16 v[26:29], v[174:177], v[138:141], v[26:29]
	v_mfma_f32_16x16x32_bf16 v[30:33], v[166:169], v[138:141], v[30:33]
	v_mfma_f32_16x16x32_bf16 v[30:33], v[170:173], v[142:145], v[30:33]
	v_mfma_f32_16x16x32_bf16 v[22:25], v[170:173], v[200:203], v[22:25]
	v_mfma_f32_16x16x32_bf16 v[22:25], v[166:169], v[196:199], v[22:25]
	v_mfma_f32_16x16x32_bf16 v[18:21], v[174:177], v[196:199], v[18:21]
	v_mfma_f32_16x16x32_bf16 v[18:21], v[162:165], v[200:203], v[18:21]
	v_mfma_f32_16x16x32_bf16 v[10:13], v[162:165], v[224:227], v[10:13]
	v_mfma_f32_16x16x32_bf16 v[10:13], v[174:177], v[220:223], v[10:13]
	v_mfma_f32_16x16x32_bf16 v[14:17], v[166:169], v[220:223], v[14:17]
	v_mfma_f32_16x16x32_bf16 v[14:17], v[170:173], v[224:227], v[14:17]
	v_mfma_f32_16x16x32_bf16 v[6:9], v[170:173], v[232:235], v[6:9]
	v_mfma_f32_16x16x32_bf16 v[6:9], v[166:169], v[228:231], v[6:9]
	s_setprio 0
	s_setprio 1
	s_and_b64 vcc, exec, s[52:53]
	s_cbranch_vccz .Lslv_b0
	v_mfma_f32_16x16x32_bf16 v[138:141], v[166:169], v[180:183], v[82:85]
	v_mfma_f32_16x16x32_bf16 v[142:145], v[174:177], v[180:183], v[94:97]
	v_mfma_f32_16x16x32_bf16 v[138:141], v[170:173], v[184:187], v[138:141]
	v_mfma_f32_16x16x32_bf16 v[142:145], v[162:165], v[184:187], v[142:145]
	s_barrier
	s_setprio 0
	s_branch .Lrot_b0

; #define PG8_STAGE(bufoff, gbase, voff) do { _Pragma("unroll") for (int _i = 0; _i < 2; ++_i) \
;         __builtin_amdgcn_global_load_lds((const unsigned*)((const char*)(gbase) + (size_t)_i * qstep + (voff)[0]), (PG8_LAS unsigned*)(lds + (bufoff) + ldsw + _i * 8192), 16, 0, 0); } while (0)
; #define PG8_LDA(dst, b, h) do { _Pragma("unroll") for (int m = 0; m < 4; ++m) _Pragma("unroll") for (int k = 0; k < 2; ++k) dst[m][k] = *(const PG8_LAS bf16x8*)(lds + PG8_SA(b, h) + aoff + m * 2048 + k * 1024); } while (0)
; #define PG8_LDB(dst, b, h) do { _Pragma("unroll") for (int n = 0; n < 2; ++n) _Pragma("unroll") for (int k = 0; k < 2; ++k) dst[n][k] = *(const PG8_LAS bf16x8*)(lds + PG8_SB(b, h) + boff + n * 2048 + k * 1024); } while (0)
; #define PG8_MMA(ai, bj, At, Bt) do { __builtin_amdgcn_s_setprio(1); _Pragma("unroll") for (int m = 0; m < 4; ++m) _Pragma("unroll") for (int n = 0; n < 2; ++n) _Pragma("unroll") for (int k = 0; k < 2; ++k) \
;         acc[ai][bj][m][n] = __builtin_amdgcn_mfma_f32_16x16x32_bf16(Bt[n][k], At[m][k], acc[ai][bj][m][n], 0, 0, 0); __builtin_amdgcn_s_setprio(0); } while (0)
; #define PG8_WAIT_V89() do { if constexpr (SLIVER) PG8_WAIT_V(9); else PG8_WAIT_V(8); } while (0)
; #define PG8_STAGE_S(b, gbase) do { if constexpr (SLIVER) __builtin_amdgcn_global_load_lds((const unsigned*)((const char*)(gbase) + voffS), (PG8_LAS unsigned*)(lds + STAGE_BYTES + (b) * 2048 + wid * 256), 4, 0, 0); } while (0)
; #define PG8_WAIT_L(n) asm volatile("s_waitcnt lgkmcnt(" #n ")" ::: "memory")
; #define PG8_BAR __builtin_amdgcn_s_barrier()
; #define PG8_SCHED __builtin_amdgcn_sched_barrier(0)
; template <class Epi, class Sched, bool ALIGN_EPI = false, bool SP2 = false, bool SLIVER = false>
; __device__ __forceinline__ void gemm_phase(PG8_LAS unsigned char* lds, const Gemm g, const Sched& S, const Epi& E) {
;     ...
;             PG8_LDB(B0, 1, 0); PG8_LDB(B1, 1, 1); PG8_SCHED; PG8_LDA(At, 1, 0); PG8_STAGE(PG8_SA(0, 1), a2 + hstep, voffA); PG8_STAGE_S(0, s2);
;             PG8_WAIT_V89(); PG8_WAIT_L(0); PG8_BAR; PG8_MMA(0, 0, At, B0); PG8_MMA(0, 1, At, B1); PG8_BAR; PG8_SCHED;
.Lrot_b0:
	s_add_u32 s68, s62, s80
	s_addc_u32 s69, s63, s81
	s_add_u32 s76, s68, 0x100
	s_addc_u32 s77, s69, 0
	s_and_b64 s[68:69], s[86:87], exec
	s_cselect_b32 s69, s85, s77
	s_cselect_b32 s68, s84, s76
	s_add_i32 s76, 0, 0x18000
	v_add_u32_e32 v82, s76, v239
	s_add_i32 s77, 0, 0x1c000
	ds_read_b128 v[146:149], v82
	ds_read_b128 v[150:153], v82 offset:1024
	ds_read_b128 v[154:157], v82 offset:2048
	ds_read_b128 v[158:161], v82 offset:3072
	v_add_u32_e32 v82, s77, v239
	ds_read_b128 v[166:169], v82
	ds_read_b128 v[170:173], v82 offset:1024
	ds_read_b128 v[174:177], v82 offset:2048
	ds_read_b128 v[162:165], v82 offset:3072
	s_mov_b32 m0, s91
	v_lshl_add_u64 v[208:209], v[194:195], 0, s[24:25]
	ds_read_b128 v[82:85], v242 offset:32768
	ds_read_b128 v[94:97], v242 offset:33792
	ds_read_b128 v[180:183], v242 offset:34816
	ds_read_b128 v[184:187], v242 offset:35840
	ds_read_b128 v[196:199], v242 offset:36864
	ds_read_b128 v[200:203], v242 offset:37888
	ds_read_b128 v[220:223], v242 offset:38912
	ds_read_b128 v[224:227], v242 offset:39936
	global_load_lds_dwordx4 v[208:209], off
	v_lshl_add_u64 v[208:209], v[194:195], 0, s[14:15]
	s_mov_b32 m0, s92
	s_nop 0
	global_load_lds_dwordx4 v[208:209], off
	v_lshl_add_u64 v[208:209], s[68:69], 0, v[214:215]
	s_mov_b32 m0, s93
	s_nop 0
	global_load_lds_dword v[208:209], off
	s_waitcnt vmcnt(9)
	s_waitcnt lgkmcnt(0)
	s_setprio 1
	s_barrier
	v_mfma_f32_16x16x32_bf16 v[134:137], v[146:149], v[82:85], v[134:137]
	v_mfma_f32_16x16x32_bf16 v[134:137], v[150:153], v[94:97], v[134:137]
	v_mfma_f32_16x16x32_bf16 v[130:133], v[158:161], v[94:97], v[130:133]
	v_mfma_f32_16x16x32_bf16 v[130:133], v[154:157], v[82:85], v[130:133]
	v_mfma_f32_16x16x32_bf16 v[122:125], v[154:157], v[180:183], v[122:125]
	v_mfma_f32_16x16x32_bf16 v[122:125], v[158:161], v[184:187], v[122:125]
	v_mfma_f32_16x16x32_bf16 v[126:129], v[150:153], v[184:187], v[126:129]
	v_mfma_f32_16x16x32_bf16 v[126:129], v[146:149], v[180:183], v[126:129]
	v_mfma_f32_16x16x32_bf16 v[118:121], v[146:149], v[196:199], v[118:121]
	v_mfma_f32_16x16x32_bf16 v[118:121], v[150:153], v[200:203], v[118:121]
	v_mfma_f32_16x16x32_bf16 v[114:117], v[158:161], v[200:203], v[114:117]
	v_mfma_f32_16x16x32_bf16 v[114:117], v[154:157], v[196:199], v[114:117]
	v_mfma_f32_16x16x32_bf16 v[106:109], v[154:157], v[220:223], v[106:109]
	v_mfma_f32_16x16x32_bf16 v[106:109], v[158:161], v[224:227], v[106:109]
	v_mfma_f32_16x16x32_bf16 v[110:113], v[150:153], v[224:227], v[110:113]
	v_mfma_f32_16x16x32_bf16 v[110:113], v[146:149], v[220:223], v[110:113]
	s_setprio 0
	v_mfma_f32_16x16x32_bf16 v[102:105], v[166:169], v[82:85], v[102:105]
	v_mfma_f32_16x16x32_bf16 v[102:105], v[170:173], v[94:97], v[102:105]
	s_setprio 1
	v_mfma_f32_16x16x32_bf16 v[82:85], v[174:177], v[82:85], v[98:101]
	v_mfma_f32_16x16x32_bf16 v[98:101], v[162:165], v[94:97], v[82:85]
	v_mfma_f32_16x16x32_bf16 v[82:85], v[166:169], v[180:183], v[90:93]
	v_mfma_f32_16x16x32_bf16 v[90:93], v[170:173], v[184:187], v[82:85]
	v_mfma_f32_16x16x32_bf16 v[82:85], v[174:177], v[180:183], v[86:89]
	v_mfma_f32_16x16x32_bf16 v[86:89], v[162:165], v[184:187], v[82:85]
	v_mfma_f32_16x16x32_bf16 v[78:81], v[166:169], v[196:199], v[78:81]
	v_mfma_f32_16x16x32_bf16 v[78:81], v[170:173], v[200:203], v[78:81]
	v_mfma_f32_16x16x32_bf16 v[74:77], v[174:177], v[196:199], v[74:77]
	v_mfma_f32_16x16x32_bf16 v[74:77], v[162:165], v[200:203], v[74:77]
	v_mfma_f32_16x16x32_bf16 v[70:73], v[166:169], v[220:223], v[70:73]
	v_mfma_f32_16x16x32_bf16 v[70:73], v[170:173], v[224:227], v[70:73]
	v_mfma_f32_16x16x32_bf16 v[66:69], v[174:177], v[220:223], v[66:69]
	v_mfma_f32_16x16x32_bf16 v[66:69], v[162:165], v[224:227], v[66:69]
	s_barrier
; #define PG8_SB(B) __builtin_amdgcn_rcpf(1.f + expneg(B))
; #define PG8_SB(B) __builtin_amdgcn_rcpf(1.f + expneg(B))
; #define PG8_STAGE(bufoff, gbase, voff) do { _Pragma("unroll") for (int _i = 0; _i < 2; ++_i) \
;         __builtin_amdgcn_global_load_lds((const unsigned*)((const char*)(gbase) + (size_t)_i * qstep + (voff)[0]), (PG8_LAS unsigned*)(lds + (bufoff) + ldsw + _i * 8192), 16, 0, 0); } while (0)
; #define PG8_LDA(dst, b, h) do { _Pragma("unroll") for (int m = 0; m < 4; ++m) _Pragma("unroll") for (int k = 0; k < 2; ++k) dst[m][k] = *(const PG8_LAS bf16x8*)(lds + PG8_SA(b, h) + aoff + m * 2048 + k * 1024); } while (0)
; #define PG8_MMA(ai, bj, At, Bt) do { __builtin_amdgcn_s_setprio(1); _Pragma("unroll") for (int m = 0; m < 4; ++m) _Pragma("unroll") for (int n = 0; n < 2; ++n) _Pragma("unroll") for (int k = 0; k < 2; ++k) \
;         acc[ai][bj][m][n] = __builtin_amdgcn_mfma_f32_16x16x32_bf16(Bt[n][k], At[m][k], acc[ai][bj][m][n], 0, 0, 0); __builtin_amdgcn_s_setprio(0); } while (0)
; #define PG8_WAIT_V89() do { if constexpr (SLIVER) PG8_WAIT_V(9); else PG8_WAIT_V(8); } while (0)
; #define PG8_LDS_S(b) do { if constexpr (SLIVER) { Sf[0] = *(const PG8_LAS bf16x8*)(lds + STAGE_BYTES + (b) * 2048 + soff0); Sf[1] = *(const PG8_LAS bf16x8*)(lds + STAGE_BYTES + (b) * 2048 + (soff0 ^ 64)); } } while (0)
; #define PG8_WAIT_L(n) asm volatile("s_waitcnt lgkmcnt(" #n ")" ::: "memory")
; #define PG8_BAR __builtin_amdgcn_s_barrier()
; #define PG8_SCHED __builtin_amdgcn_sched_barrier(0)
; template <class Epi, class Sched, bool ALIGN_EPI = false, bool SP2 = false, bool SLIVER = false>
; __device__ __forceinline__ void gemm_phase(PG8_LAS unsigned char* lds, const Gemm g, const Sched& S, const Epi& E) {
;     ...
;             PG8_LDA(At, 1, 1); PG8_LDS_S(1); PG8_STAGE(PG8_SB(1, 0), b3, voffB); PG8_STAGE(PG8_SB(1, 1), b3 + hstep, voffB); PG8_STAGE(PG8_SA(1, 0), a3, voffA);
;             PG8_WAIT_V89(); PG8_WAIT_L(0); PG8_BAR; PG8_MMA(1, 0, At, B0); PG8_MMA(1, 1, At, B1); PG8_MMA_S(); PG8_BAR; PG8_SCHED;
	s_setprio 0
	s_add_i32 s68, 0, 0x20800
	v_add_u32_e32 v178, s68, v240
	v_add_u32_e32 v184, s68, v241
	s_add_i32 s68, s76, s95
	v_lshl_add_u64 v[208:209], v[192:193], 0, s[26:27]
	s_mov_b32 m0, s68
	ds_read_b128 v[82:85], v242 offset:49152
	ds_read_b128 v[94:97], v242 offset:50176
	ds_read_b128 v[196:199], v242 offset:51200
	ds_read_b128 v[200:203], v242 offset:52224
	ds_read_b128 v[220:223], v242 offset:53248
	ds_read_b128 v[224:227], v242 offset:54272
	ds_read_b128 v[228:231], v242 offset:55296
	ds_read_b128 v[232:235], v242 offset:56320
	ds_read_b128 v[180:183], v178
	ds_read_b128 v[184:187], v184
	global_load_lds_dwordx4 v[208:209], off
	v_lshl_add_u64 v[208:209], v[192:193], 0, s[72:73]
	s_add_i32 m0, s68, 0x2000
	s_add_i32 s68, s77, s95
	global_load_lds_dwordx4 v[208:209], off
	v_lshl_add_u64 v[208:209], v[192:193], 0, s[34:35]
	s_mov_b32 m0, s68
	s_mov_b64 s[76:77], 0x120080
	global_load_lds_dwordx4 v[208:209], off
	v_lshl_add_u64 v[192:193], v[192:193], 0, s[76:77]
	s_add_i32 m0, s68, 0x2000
	s_nop 0
	global_load_lds_dwordx4 v[192:193], off
	v_lshl_add_u64 v[192:193], v[194:195], 0, s[26:27]
	s_mov_b32 m0, s97
	s_nop 0
	global_load_lds_dwordx4 v[192:193], off
	v_lshl_add_u64 v[192:193], v[194:195], 0, s[72:73]
	s_mov_b32 m0, s18
	s_nop 0
	global_load_lds_dwordx4 v[192:193], off
	s_waitcnt vmcnt(9)
	s_waitcnt lgkmcnt(0)
	s_setprio 1
	s_barrier
	v_mfma_f32_16x16x32_bf16 v[62:65], v[146:149], v[82:85], v[62:65]
	v_mfma_f32_16x16x32_bf16 v[62:65], v[150:153], v[94:97], v[62:65]
	v_mfma_f32_16x16x32_bf16 v[58:61], v[158:161], v[94:97], v[58:61]
	v_mfma_f32_16x16x32_bf16 v[58:61], v[154:157], v[82:85], v[58:61]
	v_mfma_f32_16x16x32_bf16 v[50:53], v[154:157], v[196:199], v[50:53]
	v_mfma_f32_16x16x32_bf16 v[50:53], v[158:161], v[200:203], v[50:53]
	v_mfma_f32_16x16x32_bf16 v[54:57], v[150:153], v[200:203], v[54:57]
	v_mfma_f32_16x16x32_bf16 v[54:57], v[146:149], v[196:199], v[54:57]
	v_mfma_f32_16x16x32_bf16 v[46:49], v[146:149], v[220:223], v[46:49]
	v_mfma_f32_16x16x32_bf16 v[46:49], v[150:153], v[224:227], v[46:49]
	v_mfma_f32_16x16x32_bf16 v[42:45], v[158:161], v[224:227], v[42:45]
	v_mfma_f32_16x16x32_bf16 v[42:45], v[154:157], v[220:223], v[42:45]
	v_mfma_f32_16x16x32_bf16 v[34:37], v[154:157], v[228:231], v[34:37]
	v_mfma_f32_16x16x32_bf16 v[34:37], v[158:161], v[232:235], v[34:37]
	v_mfma_f32_16x16x32_bf16 v[38:41], v[150:153], v[232:235], v[38:41]
	v_mfma_f32_16x16x32_bf16 v[38:41], v[146:149], v[228:231], v[38:41]
	s_setprio 0
	v_mfma_f32_16x16x32_bf16 v[2:5], v[174:177], v[228:231], v[2:5]
	v_mfma_f32_16x16x32_bf16 v[2:5], v[162:165], v[232:235], v[2:5]
	s_setprio 1
	v_mfma_f32_16x16x32_bf16 v[26:29], v[162:165], v[94:97], v[26:29]
	v_mfma_f32_16x16x32_bf16 v[26:29], v[174:177], v[82:85], v[26:29]
	v_mfma_f32_16x16x32_bf16 v[30:33], v[166:169], v[82:85], v[30:33]
	v_mfma_f32_16x16x32_bf16 v[30:33], v[170:173], v[94:97], v[30:33]
	v_mfma_f32_16x16x32_bf16 v[22:25], v[170:173], v[200:203], v[22:25]
	v_mfma_f32_16x16x32_bf16 v[22:25], v[166:169], v[196:199], v[22:25]
	v_mfma_f32_16x16x32_bf16 v[18:21], v[174:177], v[196:199], v[18:21]
	v_mfma_f32_16x16x32_bf16 v[18:21], v[162:165], v[200:203], v[18:21]
	v_mfma_f32_16x16x32_bf16 v[10:13], v[162:165], v[224:227], v[10:13]
	v_mfma_f32_16x16x32_bf16 v[10:13], v[174:177], v[220:223], v[10:13]
	v_mfma_f32_16x16x32_bf16 v[14:17], v[166:169], v[220:223], v[14:17]
	v_mfma_f32_16x16x32_bf16 v[14:17], v[170:173], v[224:227], v[14:17]
	v_mfma_f32_16x16x32_bf16 v[6:9], v[170:173], v[232:235], v[6:9]
	v_mfma_f32_16x16x32_bf16 v[6:9], v[166:169], v[228:231], v[6:9]
	s_setprio 0
	s_setprio 1
	s_and_b64 vcc, exec, s[52:53]
	s_cbranch_vccz .Lslv_c0
	v_mfma_f32_16x16x32_bf16 v[82:85], v[166:169], v[180:183], v[138:141]
	v_mfma_f32_16x16x32_bf16 v[94:97], v[174:177], v[180:183], v[142:145]
	v_mfma_f32_16x16x32_bf16 v[82:85], v[170:173], v[184:187], v[82:85]
	v_mfma_f32_16x16x32_bf16 v[94:97], v[162:165], v[184:187], v[94:97]
	s_barrier
	s_setprio 0
	s_branch .Lrot_c0

; #define PG8_STAGE(bufoff, gbase, voff) do { _Pragma("unroll") for (int _i = 0; _i < 2; ++_i) \
;         __builtin_amdgcn_global_load_lds((const unsigned*)((const char*)(gbase) + (size_t)_i * qstep + (voff)[0]), (PG8_LAS unsigned*)(lds + (bufoff) + ldsw + _i * 8192), 16, 0, 0); } while (0)
; #define PG8_LDA(dst, b, h) do { _Pragma("unroll") for (int m = 0; m < 4; ++m) _Pragma("unroll") for (int k = 0; k < 2; ++k) dst[m][k] = *(const PG8_LAS bf16x8*)(lds + PG8_SA(b, h) + aoff + m * 2048 + k * 1024); } while (0)
; #define PG8_LDB(dst, b, h) do { _Pragma("unroll") for (int n = 0; n < 2; ++n) _Pragma("unroll") for (int k = 0; k < 2; ++k) dst[n][k] = *(const PG8_LAS bf16x8*)(lds + PG8_SB(b, h) + boff + n * 2048 + k * 1024); } while (0)
; #define PG8_MMA(ai, bj, At, Bt) do { __builtin_amdgcn_s_setprio(1); _Pragma("unroll") for (int m = 0; m < 4; ++m) _Pragma("unroll") for (int n = 0; n < 2; ++n) _Pragma("unroll") for (int k = 0; k < 2; ++k) \
;         acc[ai][bj][m][n] = __builtin_amdgcn_mfma_f32_16x16x32_bf16(Bt[n][k], At[m][k], acc[ai][bj][m][n], 0, 0, 0); __builtin_amdgcn_s_setprio(0); } while (0)
; #define PG8_WAIT_V89() do { if constexpr (SLIVER) PG8_WAIT_V(9); else PG8_WAIT_V(8); } while (0)
; #define PG8_STAGE_S(b, gbase) do { if constexpr (SLIVER) __builtin_amdgcn_global_load_lds((const unsigned*)((const char*)(gbase) + voffS), (PG8_LAS unsigned*)(lds + STAGE_BYTES + (b) * 2048 + wid * 256), 4, 0, 0); } while (0)
; #define PG8_WAIT_L(n) asm volatile("s_waitcnt lgkmcnt(" #n ")" ::: "memory")
; #define PG8_BAR __builtin_amdgcn_s_barrier()
; #define PG8_SCHED __builtin_amdgcn_sched_barrier(0)
; template <class Epi, class Sched, bool ALIGN_EPI = false, bool SP2 = false, bool SLIVER = false>
; __device__ __forceinline__ void gemm_phase(PG8_LAS unsigned char* lds, const Gemm g, const Sched& S, const Epi& E) {
;     ...
;             PG8_LDB(B0, 0, 0); PG8_LDB(B1, 0, 1); PG8_SCHED; PG8_LDA(At, 0, 0); PG8_STAGE(PG8_SA(1, 1), a1 + hstep, voffA); PG8_STAGE_S(1, s1);
;             PG8_WAIT_V89(); PG8_WAIT_L(0); PG8_BAR; PG8_MMA(0, 0, At, B0); PG8_MMA(0, 1, At, B1); PG8_BAR; PG8_SCHED;
.LBB0_598:
	s_add_u32 s40, s92, s62
	s_addc_u32 s41, s93, s63
	s_add_u32 s77, s40, 0x100
	s_addc_u32 s78, s41, 0
	s_add_u32 s83, s68, s62
	s_addc_u32 s79, s69, s63
	s_add_i32 s96, 0, 0x10000
	s_cmpk_eq_i32 s62, 0xf00
	s_cselect_b64 s[80:81], -1, 0
	s_and_b64 s[40:41], s[80:81], exec
	s_cselect_b32 s41, s12, s78
	s_cselect_b32 s40, s13, s77
	v_add_u32_e32 v138, s96, v212
	s_cselect_b32 s79, s17, s79
	s_cselect_b32 s78, s55, s83
	s_add_i32 s77, 0, 0x14000
	ds_read_b128 v[146:149], v138
	ds_read_b128 v[150:153], v138 offset:1024
	ds_read_b128 v[154:157], v138 offset:2048
	ds_read_b128 v[158:161], v138 offset:3072
	v_add_u32_e32 v138, s77, v212
	ds_read_b128 v[166:169], v138
	ds_read_b128 v[170:173], v138 offset:1024
	ds_read_b128 v[174:177], v138 offset:2048
	ds_read_b128 v[162:165], v138 offset:3072
	v_lshl_add_u64 v[202:203], v[200:201], 0, s[62:63]
	v_lshl_add_u64 v[208:209], v[202:203], 0, s[30:31]
	s_add_i32 m0, s85, 0xc000
	ds_read_b128 v[138:141], v215
	ds_read_b128 v[142:145], v215 offset:1024
	ds_read_b128 v[180:183], v215 offset:2048
	ds_read_b128 v[184:187], v215 offset:3072
	ds_read_b128 v[216:219], v215 offset:4096
	ds_read_b128 v[220:223], v215 offset:5120
	ds_read_b128 v[224:227], v215 offset:6144
	ds_read_b128 v[228:231], v215 offset:7168
	global_load_lds_dwordx4 v[208:209], off
	v_lshl_add_u64 v[202:203], v[202:203], 0, s[34:35]
	s_add_i32 m0, s85, 0xe000
	s_nop 0
	global_load_lds_dwordx4 v[202:203], off
	v_lshl_add_u64 v[202:203], v[198:199], 0, s[62:63]
	s_add_i32 m0, s45, 0x20800
	s_nop 0
	global_load_lds_dword v[202:203], off
	s_waitcnt vmcnt(9)
	s_waitcnt lgkmcnt(0)
	s_setprio 1
	s_barrier
	v_mfma_f32_16x16x32_bf16 v[134:137], v[146:149], v[138:141], v[134:137]
	v_mfma_f32_16x16x32_bf16 v[134:137], v[150:153], v[142:145], v[134:137]
	v_mfma_f32_16x16x32_bf16 v[130:133], v[158:161], v[142:145], v[130:133]
	v_mfma_f32_16x16x32_bf16 v[130:133], v[154:157], v[138:141], v[130:133]
	v_mfma_f32_16x16x32_bf16 v[114:117], v[154:157], v[180:183], v[114:117]
	v_mfma_f32_16x16x32_bf16 v[114:117], v[158:161], v[184:187], v[114:117]
	v_mfma_f32_16x16x32_bf16 v[118:121], v[150:153], v[184:187], v[118:121]
	v_mfma_f32_16x16x32_bf16 v[118:121], v[146:149], v[180:183], v[118:121]
	v_mfma_f32_16x16x32_bf16 v[102:105], v[146:149], v[216:219], v[102:105]
	v_mfma_f32_16x16x32_bf16 v[102:105], v[150:153], v[220:223], v[102:105]
	v_mfma_f32_16x16x32_bf16 v[98:101], v[158:161], v[220:223], v[98:101]
	v_mfma_f32_16x16x32_bf16 v[98:101], v[154:157], v[216:219], v[98:101]
	v_mfma_f32_16x16x32_bf16 v[82:85], v[154:157], v[224:227], v[82:85]
	v_mfma_f32_16x16x32_bf16 v[82:85], v[158:161], v[228:231], v[82:85]
	v_mfma_f32_16x16x32_bf16 v[86:89], v[150:153], v[228:231], v[86:89]
	v_mfma_f32_16x16x32_bf16 v[86:89], v[146:149], v[224:227], v[86:89]
	s_setprio 0
	v_mfma_f32_16x16x32_bf16 v[74:77], v[174:177], v[224:227], v[74:77]
	v_mfma_f32_16x16x32_bf16 v[74:77], v[162:165], v[228:231], v[74:77]
	s_setprio 1
	v_mfma_f32_16x16x32_bf16 v[122:125], v[162:165], v[142:145], v[122:125]
	v_mfma_f32_16x16x32_bf16 v[122:125], v[174:177], v[138:141], v[122:125]
	v_mfma_f32_16x16x32_bf16 v[126:129], v[166:169], v[138:141], v[126:129]
	v_mfma_f32_16x16x32_bf16 v[126:129], v[170:173], v[142:145], v[126:129]
	v_mfma_f32_16x16x32_bf16 v[110:113], v[170:173], v[184:187], v[110:113]
	v_mfma_f32_16x16x32_bf16 v[110:113], v[166:169], v[180:183], v[110:113]
	v_mfma_f32_16x16x32_bf16 v[106:109], v[174:177], v[180:183], v[106:109]
	v_mfma_f32_16x16x32_bf16 v[106:109], v[162:165], v[184:187], v[106:109]
	v_mfma_f32_16x16x32_bf16 v[90:93], v[162:165], v[220:223], v[90:93]
	v_mfma_f32_16x16x32_bf16 v[90:93], v[174:177], v[216:219], v[90:93]
	v_mfma_f32_16x16x32_bf16 v[94:97], v[166:169], v[216:219], v[94:97]
	v_mfma_f32_16x16x32_bf16 v[94:97], v[170:173], v[220:223], v[94:97]
	v_mfma_f32_16x16x32_bf16 v[78:81], v[170:173], v[228:231], v[78:81]
	v_mfma_f32_16x16x32_bf16 v[78:81], v[166:169], v[224:227], v[78:81]
	s_barrier
; #define PG8_SB(B) __builtin_amdgcn_rcpf(1.f + expneg(B))
; #define PG8_SB(B) __builtin_amdgcn_rcpf(1.f + expneg(B))
; #define PG8_STAGE(bufoff, gbase, voff) do { _Pragma("unroll") for (int _i = 0; _i < 2; ++_i) \
;         __builtin_amdgcn_global_load_lds((const unsigned*)((const char*)(gbase) + (size_t)_i * qstep + (voff)[0]), (PG8_LAS unsigned*)(lds + (bufoff) + ldsw + _i * 8192), 16, 0, 0); } while (0)
; #define PG8_LDA(dst, b, h) do { _Pragma("unroll") for (int m = 0; m < 4; ++m) _Pragma("unroll") for (int k = 0; k < 2; ++k) dst[m][k] = *(const PG8_LAS bf16x8*)(lds + PG8_SA(b, h) + aoff + m * 2048 + k * 1024); } while (0)
; #define PG8_MMA(ai, bj, At, Bt) do { __builtin_amdgcn_s_setprio(1); _Pragma("unroll") for (int m = 0; m < 4; ++m) _Pragma("unroll") for (int n = 0; n < 2; ++n) _Pragma("unroll") for (int k = 0; k < 2; ++k) \
;         acc[ai][bj][m][n] = __builtin_amdgcn_mfma_f32_16x16x32_bf16(Bt[n][k], At[m][k], acc[ai][bj][m][n], 0, 0, 0); __builtin_amdgcn_s_setprio(0); } while (0)
; #define PG8_WAIT_V89() do { if constexpr (SLIVER) PG8_WAIT_V(9); else PG8_WAIT_V(8); } while (0)
; #define PG8_LDS_S(b) do { if constexpr (SLIVER) { Sf[0] = *(const PG8_LAS bf16x8*)(lds + STAGE_BYTES + (b) * 2048 + soff0); Sf[1] = *(const PG8_LAS bf16x8*)(lds + STAGE_BYTES + (b) * 2048 + (soff0 ^ 64)); } } while (0)
; #define PG8_WAIT_L(n) asm volatile("s_waitcnt lgkmcnt(" #n ")" ::: "memory")
; #define PG8_BAR __builtin_amdgcn_s_barrier()
; #define PG8_SCHED __builtin_amdgcn_sched_barrier(0)
; template <class Epi, class Sched, bool ALIGN_EPI = false, bool SP2 = false, bool SLIVER = false>
; __device__ __forceinline__ void gemm_phase(PG8_LAS unsigned char* lds, const Gemm g, const Sched& S, const Epi& E) {
;     ...
;             PG8_LDA(At, 0, 1); PG8_LDS_S(0); PG8_STAGE(PG8_SB(0, 0), b2, voffB); PG8_STAGE(PG8_SB(0, 1), b2 + hstep, voffB); PG8_STAGE(PG8_SA(0, 0), a2, voffA);
;             PG8_WAIT_V89(); PG8_WAIT_L(0); PG8_BAR; PG8_MMA(1, 0, At, B0); PG8_MMA(1, 1, At, B1); PG8_MMA_S(); PG8_BAR; PG8_SCHED;
	s_setprio 0
	s_add_i32 s83, 0, 0x20000
	v_lshl_add_u64 v[202:203], s[78:79], 0, v[190:191]
	s_add_i32 s78, s96, s18
	v_add_u32_e32 v178, s83, v213
	v_add_u32_e32 v184, s83, v214
	s_mov_b32 m0, s78
	ds_read_b128 v[138:141], v215 offset:16384
	ds_read_b128 v[142:145], v215 offset:17408
	ds_read_b128 v[216:219], v215 offset:18432
	ds_read_b128 v[220:223], v215 offset:19456
	ds_read_b128 v[224:227], v215 offset:20480
	ds_read_b128 v[228:231], v215 offset:21504
	ds_read_b128 v[232:235], v215 offset:22528
	ds_read_b128 v[240:243], v215 offset:23552
	ds_read_b128 v[180:183], v178
	ds_read_b128 v[184:187], v184
	global_load_lds_dwordx4 v[202:203], off
	v_lshl_add_u64 v[208:209], v[202:203], 0, s[20:21]
	s_add_i32 m0, s78, 0x2000
	s_add_i32 s77, s77, s18
	global_load_lds_dwordx4 v[208:209], off
	v_lshl_add_u64 v[208:209], v[202:203], 0, s[22:23]
	s_mov_b32 m0, s77
	v_lshl_add_u64 v[210:211], s[40:41], 0, v[188:189]
	global_load_lds_dwordx4 v[208:209], off
	v_lshl_add_u64 v[208:209], v[202:203], 0, s[24:25]
	s_add_i32 m0, s77, 0x2000
	s_nop 0
	global_load_lds_dwordx4 v[208:209], off
	s_mov_b32 m0, s85
	v_lshl_add_u64 v[208:209], v[210:211], 0, s[20:21]
	global_load_lds_dwordx4 v[210:211], off
	s_mov_b32 m0, s19
	s_nop 0
	global_load_lds_dwordx4 v[208:209], off
	s_waitcnt vmcnt(9)
	s_waitcnt lgkmcnt(0)
	s_setprio 1
	s_barrier
	v_mfma_f32_16x16x32_bf16 v[70:73], v[146:149], v[138:141], v[70:73]
	v_mfma_f32_16x16x32_bf16 v[70:73], v[150:153], v[142:145], v[70:73]
	v_mfma_f32_16x16x32_bf16 v[66:69], v[158:161], v[142:145], v[66:69]
	v_mfma_f32_16x16x32_bf16 v[66:69], v[154:157], v[138:141], v[66:69]
	v_mfma_f32_16x16x32_bf16 v[50:53], v[154:157], v[216:219], v[50:53]
	v_mfma_f32_16x16x32_bf16 v[50:53], v[158:161], v[220:223], v[50:53]
	v_mfma_f32_16x16x32_bf16 v[54:57], v[150:153], v[220:223], v[54:57]
	v_mfma_f32_16x16x32_bf16 v[54:57], v[146:149], v[216:219], v[54:57]
	v_mfma_f32_16x16x32_bf16 v[38:41], v[146:149], v[224:227], v[38:41]
	v_mfma_f32_16x16x32_bf16 v[38:41], v[150:153], v[228:231], v[38:41]
	v_mfma_f32_16x16x32_bf16 v[34:37], v[158:161], v[228:231], v[34:37]
	v_mfma_f32_16x16x32_bf16 v[34:37], v[154:157], v[224:227], v[34:37]
	v_mfma_f32_16x16x32_bf16 v[18:21], v[154:157], v[232:235], v[18:21]
	v_mfma_f32_16x16x32_bf16 v[18:21], v[158:161], v[240:243], v[18:21]
	v_mfma_f32_16x16x32_bf16 v[22:25], v[150:153], v[240:243], v[22:25]
	v_mfma_f32_16x16x32_bf16 v[22:25], v[146:149], v[232:235], v[22:25]
	s_setprio 0
	v_mfma_f32_16x16x32_bf16 v[10:13], v[174:177], v[232:235], v[10:13]
	v_mfma_f32_16x16x32_bf16 v[10:13], v[162:165], v[240:243], v[10:13]
	s_setprio 1
	v_mfma_f32_16x16x32_bf16 v[58:61], v[162:165], v[142:145], v[58:61]
	v_mfma_f32_16x16x32_bf16 v[58:61], v[174:177], v[138:141], v[58:61]
	v_mfma_f32_16x16x32_bf16 v[62:65], v[166:169], v[138:141], v[62:65]
	v_mfma_f32_16x16x32_bf16 v[62:65], v[170:173], v[142:145], v[62:65]
	v_mfma_f32_16x16x32_bf16 v[46:49], v[170:173], v[220:223], v[46:49]
	v_mfma_f32_16x16x32_bf16 v[46:49], v[166:169], v[216:219], v[46:49]
	v_mfma_f32_16x16x32_bf16 v[42:45], v[174:177], v[216:219], v[42:45]
	v_mfma_f32_16x16x32_bf16 v[42:45], v[162:165], v[220:223], v[42:45]
	v_mfma_f32_16x16x32_bf16 v[26:29], v[162:165], v[228:231], v[26:29]
	v_mfma_f32_16x16x32_bf16 v[26:29], v[174:177], v[224:227], v[26:29]
	v_mfma_f32_16x16x32_bf16 v[30:33], v[166:169], v[224:227], v[30:33]
	v_mfma_f32_16x16x32_bf16 v[30:33], v[170:173], v[228:231], v[30:33]
	v_mfma_f32_16x16x32_bf16 v[14:17], v[170:173], v[240:243], v[14:17]
	v_mfma_f32_16x16x32_bf16 v[14:17], v[166:169], v[232:235], v[14:17]
	s_setprio 0
	s_setprio 1
	s_and_b64 vcc, exec, s[52:53]
	s_cbranch_vccz .Lslv_b1
	v_mfma_f32_16x16x32_bf16 v[138:141], v[166:169], v[180:183], v[6:9]
	v_mfma_f32_16x16x32_bf16 v[142:145], v[174:177], v[180:183], v[2:5]
	v_mfma_f32_16x16x32_bf16 v[138:141], v[170:173], v[184:187], v[138:141]
	v_mfma_f32_16x16x32_bf16 v[142:145], v[162:165], v[184:187], v[142:145]
	s_barrier
	s_setprio 0
	s_branch .Lrot_b1

; #define PG8_STAGE(bufoff, gbase, voff) do { _Pragma("unroll") for (int _i = 0; _i < 2; ++_i) \
;         __builtin_amdgcn_global_load_lds((const unsigned*)((const char*)(gbase) + (size_t)_i * qstep + (voff)[0]), (PG8_LAS unsigned*)(lds + (bufoff) + ldsw + _i * 8192), 16, 0, 0); } while (0)
; #define PG8_LDA(dst, b, h) do { _Pragma("unroll") for (int m = 0; m < 4; ++m) _Pragma("unroll") for (int k = 0; k < 2; ++k) dst[m][k] = *(const PG8_LAS bf16x8*)(lds + PG8_SA(b, h) + aoff + m * 2048 + k * 1024); } while (0)
; #define PG8_LDB(dst, b, h) do { _Pragma("unroll") for (int n = 0; n < 2; ++n) _Pragma("unroll") for (int k = 0; k < 2; ++k) dst[n][k] = *(const PG8_LAS bf16x8*)(lds + PG8_SB(b, h) + boff + n * 2048 + k * 1024); } while (0)
; #define PG8_MMA(ai, bj, At, Bt) do { __builtin_amdgcn_s_setprio(1); _Pragma("unroll") for (int m = 0; m < 4; ++m) _Pragma("unroll") for (int n = 0; n < 2; ++n) _Pragma("unroll") for (int k = 0; k < 2; ++k) \
;         acc[ai][bj][m][n] = __builtin_amdgcn_mfma_f32_16x16x32_bf16(Bt[n][k], At[m][k], acc[ai][bj][m][n], 0, 0, 0); __builtin_amdgcn_s_setprio(0); } while (0)
; #define PG8_WAIT_V89() do { if constexpr (SLIVER) PG8_WAIT_V(9); else PG8_WAIT_V(8); } while (0)
; #define PG8_STAGE_S(b, gbase) do { if constexpr (SLIVER) __builtin_amdgcn_global_load_lds((const unsigned*)((const char*)(gbase) + voffS), (PG8_LAS unsigned*)(lds + STAGE_BYTES + (b) * 2048 + wid * 256), 4, 0, 0); } while (0)
; #define PG8_WAIT_L(n) asm volatile("s_waitcnt lgkmcnt(" #n ")" ::: "memory")
; #define PG8_BAR __builtin_amdgcn_s_barrier()
; #define PG8_SCHED __builtin_amdgcn_sched_barrier(0)
; template <class Epi, class Sched, bool ALIGN_EPI = false, bool SP2 = false, bool SLIVER = false>
; __device__ __forceinline__ void gemm_phase(PG8_LAS unsigned char* lds, const Gemm g, const Sched& S, const Epi& E) {
;     ...
;             PG8_LDB(B0, 1, 0); PG8_LDB(B1, 1, 1); PG8_SCHED; PG8_LDA(At, 1, 0); PG8_STAGE(PG8_SA(0, 1), a2 + hstep, voffA); PG8_STAGE_S(0, s2);
;             PG8_WAIT_V89(); PG8_WAIT_L(0); PG8_BAR; PG8_MMA(0, 0, At, B0); PG8_MMA(0, 1, At, B1); PG8_BAR; PG8_SCHED;
.Lrot_b1:
	s_add_u32 s77, s94, s62
	s_addc_u32 s78, s95, s63
	s_add_u32 s77, s77, 0x100
	s_addc_u32 s83, s78, 0
	s_and_b64 s[78:79], s[80:81], exec
	s_cselect_b32 s79, s66, s83
	s_cselect_b32 s78, s67, s77
	s_add_i32 s77, 0, 0x18000
	v_add_u32_e32 v2, s77, v212
	s_add_i32 s80, 0, 0x1c000
	ds_read_b128 v[146:149], v2
	ds_read_b128 v[150:153], v2 offset:1024
	ds_read_b128 v[154:157], v2 offset:2048
	ds_read_b128 v[158:161], v2 offset:3072
	v_add_u32_e32 v2, s80, v212
	ds_read_b128 v[166:169], v2
	ds_read_b128 v[170:173], v2 offset:1024
	ds_read_b128 v[174:177], v2 offset:2048
	ds_read_b128 v[162:165], v2 offset:3072
	s_mov_b32 m0, s49
	v_lshl_add_u64 v[208:209], v[210:211], 0, s[22:23]
	ds_read_b128 v[2:5], v215 offset:32768
	ds_read_b128 v[6:9], v215 offset:33792
	ds_read_b128 v[180:183], v215 offset:34816
	ds_read_b128 v[184:187], v215 offset:35840
	ds_read_b128 v[216:219], v215 offset:36864
	ds_read_b128 v[220:223], v215 offset:37888
	ds_read_b128 v[224:227], v215 offset:38912
	ds_read_b128 v[228:231], v215 offset:39936
	global_load_lds_dwordx4 v[208:209], off
	v_lshl_add_u64 v[208:209], v[210:211], 0, s[24:25]
	s_mov_b32 m0, s50
	s_nop 0
	global_load_lds_dwordx4 v[208:209], off
	v_lshl_add_u64 v[208:209], s[78:79], 0, v[192:193]
	s_mov_b32 m0, s51
	s_nop 0
	global_load_lds_dword v[208:209], off
	s_waitcnt vmcnt(9)
	s_waitcnt lgkmcnt(0)
	s_setprio 1
	s_barrier
	v_mfma_f32_16x16x32_bf16 v[134:137], v[146:149], v[2:5], v[134:137]
	v_mfma_f32_16x16x32_bf16 v[134:137], v[150:153], v[6:9], v[134:137]
	v_mfma_f32_16x16x32_bf16 v[130:133], v[158:161], v[6:9], v[130:133]
	v_mfma_f32_16x16x32_bf16 v[130:133], v[154:157], v[2:5], v[130:133]
	v_mfma_f32_16x16x32_bf16 v[114:117], v[154:157], v[180:183], v[114:117]
	v_mfma_f32_16x16x32_bf16 v[114:117], v[158:161], v[184:187], v[114:117]
	v_mfma_f32_16x16x32_bf16 v[118:121], v[150:153], v[184:187], v[118:121]
	v_mfma_f32_16x16x32_bf16 v[118:121], v[146:149], v[180:183], v[118:121]
	v_mfma_f32_16x16x32_bf16 v[102:105], v[146:149], v[216:219], v[102:105]
	v_mfma_f32_16x16x32_bf16 v[102:105], v[150:153], v[220:223], v[102:105]
	v_mfma_f32_16x16x32_bf16 v[98:101], v[158:161], v[220:223], v[98:101]
	v_mfma_f32_16x16x32_bf16 v[98:101], v[154:157], v[216:219], v[98:101]
	v_mfma_f32_16x16x32_bf16 v[82:85], v[154:157], v[224:227], v[82:85]
	v_mfma_f32_16x16x32_bf16 v[82:85], v[158:161], v[228:231], v[82:85]
	v_mfma_f32_16x16x32_bf16 v[86:89], v[150:153], v[228:231], v[86:89]
	v_mfma_f32_16x16x32_bf16 v[86:89], v[146:149], v[224:227], v[86:89]
	s_setprio 0
	v_mfma_f32_16x16x32_bf16 v[126:129], v[166:169], v[2:5], v[126:129]
	v_mfma_f32_16x16x32_bf16 v[126:129], v[170:173], v[6:9], v[126:129]
	s_setprio 1
	v_mfma_f32_16x16x32_bf16 v[2:5], v[174:177], v[2:5], v[122:125]
	v_mfma_f32_16x16x32_bf16 v[122:125], v[162:165], v[6:9], v[2:5]
	v_mfma_f32_16x16x32_bf16 v[2:5], v[166:169], v[180:183], v[110:113]
	v_mfma_f32_16x16x32_bf16 v[110:113], v[170:173], v[184:187], v[2:5]
	v_mfma_f32_16x16x32_bf16 v[2:5], v[174:177], v[180:183], v[106:109]
	v_mfma_f32_16x16x32_bf16 v[106:109], v[162:165], v[184:187], v[2:5]
	v_mfma_f32_16x16x32_bf16 v[2:5], v[166:169], v[216:219], v[94:97]
	v_mfma_f32_16x16x32_bf16 v[94:97], v[170:173], v[220:223], v[2:5]
	v_mfma_f32_16x16x32_bf16 v[2:5], v[174:177], v[216:219], v[90:93]
	v_mfma_f32_16x16x32_bf16 v[90:93], v[162:165], v[220:223], v[2:5]
	v_mfma_f32_16x16x32_bf16 v[2:5], v[166:169], v[224:227], v[78:81]
	v_mfma_f32_16x16x32_bf16 v[78:81], v[170:173], v[228:231], v[2:5]
	v_mfma_f32_16x16x32_bf16 v[2:5], v[174:177], v[224:227], v[74:77]
	v_mfma_f32_16x16x32_bf16 v[74:77], v[162:165], v[228:231], v[2:5]
	s_barrier
; #define PG8_SB(B) __builtin_amdgcn_rcpf(1.f + expneg(B))
; #define PG8_SB(B) __builtin_amdgcn_rcpf(1.f + expneg(B))
; #define PG8_STAGE(bufoff, gbase, voff) do { _Pragma("unroll") for (int _i = 0; _i < 2; ++_i) \
;         __builtin_amdgcn_global_load_lds((const unsigned*)((const char*)(gbase) + (size_t)_i * qstep + (voff)[0]), (PG8_LAS unsigned*)(lds + (bufoff) + ldsw + _i * 8192), 16, 0, 0); } while (0)
; #define PG8_LDA(dst, b, h) do { _Pragma("unroll") for (int m = 0; m < 4; ++m) _Pragma("unroll") for (int k = 0; k < 2; ++k) dst[m][k] = *(const PG8_LAS bf16x8*)(lds + PG8_SA(b, h) + aoff + m * 2048 + k * 1024); } while (0)
; #define PG8_MMA(ai, bj, At, Bt) do { __builtin_amdgcn_s_setprio(1); _Pragma("unroll") for (int m = 0; m < 4; ++m) _Pragma("unroll") for (int n = 0; n < 2; ++n) _Pragma("unroll") for (int k = 0; k < 2; ++k) \
;         acc[ai][bj][m][n] = __builtin_amdgcn_mfma_f32_16x16x32_bf16(Bt[n][k], At[m][k], acc[ai][bj][m][n], 0, 0, 0); __builtin_amdgcn_s_setprio(0); } while (0)
; #define PG8_WAIT_V89() do { if constexpr (SLIVER) PG8_WAIT_V(9); else PG8_WAIT_V(8); } while (0)
; #define PG8_LDS_S(b) do { if constexpr (SLIVER) { Sf[0] = *(const PG8_LAS bf16x8*)(lds + STAGE_BYTES + (b) * 2048 + soff0); Sf[1] = *(const PG8_LAS bf16x8*)(lds + STAGE_BYTES + (b) * 2048 + (soff0 ^ 64)); } } while (0)
; #define PG8_WAIT_L(n) asm volatile("s_waitcnt lgkmcnt(" #n ")" ::: "memory")
; #define PG8_BAR __builtin_amdgcn_s_barrier()
; #define PG8_SCHED __builtin_amdgcn_sched_barrier(0)
; template <class Epi, class Sched, bool ALIGN_EPI = false, bool SP2 = false, bool SLIVER = false>
; __device__ __forceinline__ void gemm_phase(PG8_LAS unsigned char* lds, const Gemm g, const Sched& S, const Epi& E) {
;     ...
;             PG8_LDA(At, 1, 1); PG8_LDS_S(1); PG8_STAGE(PG8_SB(1, 0), b3, voffB); PG8_STAGE(PG8_SB(1, 1), b3 + hstep, voffB); PG8_STAGE(PG8_SA(1, 0), a3, voffA);
;             PG8_WAIT_V89(); PG8_WAIT_L(0); PG8_BAR; PG8_MMA(1, 0, At, B0); PG8_MMA(1, 1, At, B1); PG8_MMA_S(); PG8_BAR; PG8_SCHED;
	s_setprio 0
	s_add_i32 s78, 0, 0x20800
	s_add_i32 s77, s77, s18
	v_add_u32_e32 v178, s78, v213
	v_add_u32_e32 v184, s78, v214
	v_lshl_add_u64 v[208:209], v[202:203], 0, s[26:27]
	s_mov_b32 m0, s77
	ds_read_b128 v[2:5], v215 offset:49152
	ds_read_b128 v[6:9], v215 offset:50176
	ds_read_b128 v[216:219], v215 offset:51200
	ds_read_b128 v[220:223], v215 offset:52224
	ds_read_b128 v[224:227], v215 offset:53248
	ds_read_b128 v[228:231], v215 offset:54272
	ds_read_b128 v[232:235], v215 offset:55296
	ds_read_b128 v[240:243], v215 offset:56320
	ds_read_b128 v[180:183], v178
	ds_read_b128 v[184:187], v184
	global_load_lds_dwordx4 v[208:209], off
	v_lshl_add_u64 v[208:209], v[202:203], 0, s[28:29]
	s_add_i32 m0, s77, 0x2000
	s_add_i32 s77, s80, s18
	global_load_lds_dwordx4 v[208:209], off
	v_lshl_add_u64 v[208:209], v[202:203], 0, s[30:31]
	s_mov_b32 m0, s77
	v_lshl_add_u64 v[202:203], v[202:203], 0, s[34:35]
	global_load_lds_dwordx4 v[208:209], off
	s_add_i32 m0, s77, 0x2000
	s_nop 0
	global_load_lds_dwordx4 v[202:203], off
	v_lshl_add_u64 v[202:203], v[210:211], 0, s[26:27]
	s_mov_b32 m0, s10
	s_nop 0
	global_load_lds_dwordx4 v[202:203], off
	v_lshl_add_u64 v[202:203], v[210:211], 0, s[28:29]
	s_mov_b32 m0, s2
	s_nop 0
	global_load_lds_dwordx4 v[202:203], off
	s_waitcnt vmcnt(9)
	s_waitcnt lgkmcnt(0)
	s_setprio 1
	s_barrier
	v_mfma_f32_16x16x32_bf16 v[70:73], v[146:149], v[2:5], v[70:73]
	v_mfma_f32_16x16x32_bf16 v[70:73], v[150:153], v[6:9], v[70:73]
	v_mfma_f32_16x16x32_bf16 v[66:69], v[158:161], v[6:9], v[66:69]
	v_mfma_f32_16x16x32_bf16 v[66:69], v[154:157], v[2:5], v[66:69]
	v_mfma_f32_16x16x32_bf16 v[50:53], v[154:157], v[216:219], v[50:53]
	v_mfma_f32_16x16x32_bf16 v[50:53], v[158:161], v[220:223], v[50:53]
	v_mfma_f32_16x16x32_bf16 v[54:57], v[150:153], v[220:223], v[54:57]
	v_mfma_f32_16x16x32_bf16 v[54:57], v[146:149], v[216:219], v[54:57]
	v_mfma_f32_16x16x32_bf16 v[38:41], v[146:149], v[224:227], v[38:41]
	v_mfma_f32_16x16x32_bf16 v[38:41], v[150:153], v[228:231], v[38:41]
	v_mfma_f32_16x16x32_bf16 v[34:37], v[158:161], v[228:231], v[34:37]
	v_mfma_f32_16x16x32_bf16 v[34:37], v[154:157], v[224:227], v[34:37]
	v_mfma_f32_16x16x32_bf16 v[18:21], v[154:157], v[232:235], v[18:21]
	v_mfma_f32_16x16x32_bf16 v[18:21], v[158:161], v[240:243], v[18:21]
	v_mfma_f32_16x16x32_bf16 v[22:25], v[150:153], v[240:243], v[22:25]
	v_mfma_f32_16x16x32_bf16 v[22:25], v[146:149], v[232:235], v[22:25]
	s_setprio 0
	v_mfma_f32_16x16x32_bf16 v[62:65], v[166:169], v[2:5], v[62:65]
	v_mfma_f32_16x16x32_bf16 v[62:65], v[170:173], v[6:9], v[62:65]
	s_setprio 1
	v_mfma_f32_16x16x32_bf16 v[2:5], v[174:177], v[2:5], v[58:61]
	v_mfma_f32_16x16x32_bf16 v[58:61], v[162:165], v[6:9], v[2:5]
	v_mfma_f32_16x16x32_bf16 v[2:5], v[166:169], v[216:219], v[46:49]
	v_mfma_f32_16x16x32_bf16 v[46:49], v[170:173], v[220:223], v[2:5]
	v_mfma_f32_16x16x32_bf16 v[2:5], v[174:177], v[216:219], v[42:45]
	v_mfma_f32_16x16x32_bf16 v[42:45], v[162:165], v[220:223], v[2:5]
	v_mfma_f32_16x16x32_bf16 v[2:5], v[166:169], v[224:227], v[30:33]
	v_mfma_f32_16x16x32_bf16 v[30:33], v[170:173], v[228:231], v[2:5]
	v_mfma_f32_16x16x32_bf16 v[2:5], v[174:177], v[224:227], v[26:29]
	v_mfma_f32_16x16x32_bf16 v[26:29], v[162:165], v[228:231], v[2:5]
	v_mfma_f32_16x16x32_bf16 v[2:5], v[166:169], v[232:235], v[14:17]
	v_mfma_f32_16x16x32_bf16 v[14:17], v[170:173], v[240:243], v[2:5]
	v_mfma_f32_16x16x32_bf16 v[2:5], v[174:177], v[232:235], v[10:13]
	v_mfma_f32_16x16x32_bf16 v[10:13], v[162:165], v[240:243], v[2:5]
	s_setprio 0
	s_setprio 1
	s_and_b64 vcc, exec, s[52:53]
	s_cbranch_vccz .Lslv_c1
	v_mfma_f32_16x16x32_bf16 v[2:5], v[166:169], v[180:183], v[138:141]
	v_mfma_f32_16x16x32_bf16 v[6:9], v[170:173], v[184:187], v[2:5]
	v_mfma_f32_16x16x32_bf16 v[2:5], v[174:177], v[180:183], v[142:145]
	v_mfma_f32_16x16x32_bf16 v[2:5], v[162:165], v[184:187], v[2:5]
	s_barrier
	s_setprio 0
	s_branch .Lrot_c1

; #define PG8_STAGE(bufoff, gbase, voff) do { _Pragma("unroll") for (int _i = 0; _i < 2; ++_i) \
;         __builtin_amdgcn_global_load_lds((const unsigned*)((const char*)(gbase) + (size_t)_i * qstep + (voff)[0]), (PG8_LAS unsigned*)(lds + (bufoff) + ldsw + _i * 8192), 16, 0, 0); } while (0)
; #define PG8_LDA(dst, b, h) do { _Pragma("unroll") for (int m = 0; m < 4; ++m) _Pragma("unroll") for (int k = 0; k < 2; ++k) dst[m][k] = *(const PG8_LAS bf16x8*)(lds + PG8_SA(b, h) + aoff + m * 2048 + k * 1024); } while (0)
; #define PG8_LDB(dst, b, h) do { _Pragma("unroll") for (int n = 0; n < 2; ++n) _Pragma("unroll") for (int k = 0; k < 2; ++k) dst[n][k] = *(const PG8_LAS bf16x8*)(lds + PG8_SB(b, h) + boff + n * 2048 + k * 1024); } while (0)
; #define PG8_MMA(ai, bj, At, Bt) do { __builtin_amdgcn_s_setprio(1); _Pragma("unroll") for (int m = 0; m < 4; ++m) _Pragma("unroll") for (int n = 0; n < 2; ++n) _Pragma("unroll") for (int k = 0; k < 2; ++k) \
;         acc[ai][bj][m][n] = __builtin_amdgcn_mfma_f32_16x16x32_bf16(Bt[n][k], At[m][k], acc[ai][bj][m][n], 0, 0, 0); __builtin_amdgcn_s_setprio(0); } while (0)
; #define PG8_WAIT_V89() do { if constexpr (SLIVER) PG8_WAIT_V(9); else PG8_WAIT_V(8); } while (0)
; #define PG8_STAGE_S(b, gbase) do { if constexpr (SLIVER) __builtin_amdgcn_global_load_lds((const unsigned*)((const char*)(gbase) + voffS), (PG8_LAS unsigned*)(lds + STAGE_BYTES + (b) * 2048 + wid * 256), 4, 0, 0); } while (0)
; #define PG8_WAIT_L(n) asm volatile("s_waitcnt lgkmcnt(" #n ")" ::: "memory")
; #define PG8_BAR __builtin_amdgcn_s_barrier()
; #define PG8_SCHED __builtin_amdgcn_sched_barrier(0)
; template <class Epi, class Sched, bool ALIGN_EPI = false, bool SP2 = false, bool SLIVER = false>
; __device__ __forceinline__ void gemm_phase(PG8_LAS unsigned char* lds, const Gemm g, const Sched& S, const Epi& E) {
;     ...
;             PG8_LDB(B0, 0, 0); PG8_LDB(B1, 0, 1); PG8_SCHED; PG8_LDA(At, 0, 0); PG8_STAGE(PG8_SA(1, 1), a1 + hstep, voffA); PG8_STAGE_S(1, s1);
;             PG8_WAIT_V89(); PG8_WAIT_L(0); PG8_BAR; PG8_MMA(0, 0, At, B0); PG8_MMA(0, 1, At, B1); PG8_BAR; PG8_SCHED;
.LBB0_811:
	s_add_u32 s13, s90, s62
	s_addc_u32 s40, s91, s63
	s_add_u32 s13, s13, 0x100
	s_addc_u32 s66, s40, 0
	s_add_u32 s68, s2, s62
	s_addc_u32 s67, s3, s63
	s_add_i32 s69, 0, 0x10000
	s_cmpk_eq_i32 s62, 0x2b00
	s_cselect_b64 s[80:81], -1, 0
	s_and_b64 s[40:41], s[80:81], exec
	s_cselect_b32 s41, s85, s66
	s_cselect_b32 s40, s84, s13
	v_add_u32_e32 v66, s69, v220
	s_cselect_b32 s67, s87, s67
	s_cselect_b32 s66, s86, s68
	s_add_i32 s13, 0, 0x14000
	ds_read_b128 v[154:157], v66
	ds_read_b128 v[158:161], v66 offset:1024
	ds_read_b128 v[162:165], v66 offset:2048
	ds_read_b128 v[174:177], v66 offset:3072
	v_add_u32_e32 v66, s13, v220
	ds_read_b128 v[184:187], v66
	ds_read_b128 v[188:191], v66 offset:1024
	ds_read_b128 v[192:195], v66 offset:2048
	ds_read_b128 v[180:183], v66 offset:3072
	v_lshl_add_u64 v[146:147], v[214:215], 0, s[62:63]
	v_lshl_add_u64 v[148:149], v[146:147], 0, s[8:9]
	s_add_i32 m0, s19, 0xc000
	s_mov_b64 s[94:95], 0x210080
	ds_read_b128 v[66:69], v223
	ds_read_b128 v[70:73], v223 offset:1024
	ds_read_b128 v[74:77], v223 offset:2048
	ds_read_b128 v[78:81], v223 offset:3072
	ds_read_b128 v[216:219], v223 offset:4096
	ds_read_b128 v[224:227], v223 offset:5120
	ds_read_b128 v[228:231], v223 offset:6144
	ds_read_b128 v[232:235], v223 offset:7168
	global_load_lds_dwordx4 v[148:149], off
	v_lshl_add_u64 v[146:147], v[146:147], 0, s[94:95]
	s_add_i32 m0, s19, 0xe000
	s_nop 0
	global_load_lds_dwordx4 v[146:147], off
	v_lshl_add_u64 v[146:147], v[212:213], 0, s[62:63]
	s_add_i32 m0, s96, 0x20800
	s_nop 0
	global_load_lds_dword v[146:147], off
	s_waitcnt vmcnt(9)
	s_waitcnt lgkmcnt(0)
	s_setprio 1
	s_barrier
	v_mfma_f32_16x16x32_bf16 v[146:149], v[154:157], v[66:69], v[170:173]
	v_mfma_f32_16x16x32_bf16 v[146:149], v[158:161], v[70:73], v[146:149]
	v_mfma_f32_16x16x32_bf16 v[150:153], v[162:165], v[66:69], v[166:169]
	v_mfma_f32_16x16x32_bf16 v[150:153], v[174:177], v[70:73], v[150:153]
	v_mfma_f32_16x16x32_bf16 v[134:137], v[154:157], v[74:77], v[134:137]
	v_mfma_f32_16x16x32_bf16 v[134:137], v[158:161], v[78:81], v[134:137]
	v_mfma_f32_16x16x32_bf16 v[130:133], v[162:165], v[74:77], v[130:133]
	v_mfma_f32_16x16x32_bf16 v[130:133], v[174:177], v[78:81], v[130:133]
	v_mfma_f32_16x16x32_bf16 v[118:121], v[154:157], v[216:219], v[118:121]
	v_mfma_f32_16x16x32_bf16 v[118:121], v[158:161], v[224:227], v[118:121]
	v_mfma_f32_16x16x32_bf16 v[114:117], v[162:165], v[216:219], v[114:117]
	v_mfma_f32_16x16x32_bf16 v[114:117], v[174:177], v[224:227], v[114:117]
	v_mfma_f32_16x16x32_bf16 v[102:105], v[154:157], v[228:231], v[102:105]
	v_mfma_f32_16x16x32_bf16 v[102:105], v[158:161], v[232:235], v[102:105]
	v_mfma_f32_16x16x32_bf16 v[98:101], v[162:165], v[228:231], v[98:101]
	v_mfma_f32_16x16x32_bf16 v[98:101], v[174:177], v[232:235], v[98:101]
	s_setprio 0
	v_mfma_f32_16x16x32_bf16 v[142:145], v[184:187], v[66:69], v[142:145]
	v_mfma_f32_16x16x32_bf16 v[142:145], v[188:191], v[70:73], v[142:145]
	s_setprio 1
	v_mfma_f32_16x16x32_bf16 v[66:69], v[192:195], v[66:69], v[138:141]
	v_mfma_f32_16x16x32_bf16 v[138:141], v[180:183], v[70:73], v[66:69]
	v_mfma_f32_16x16x32_bf16 v[66:69], v[184:187], v[74:77], v[126:129]
	v_mfma_f32_16x16x32_bf16 v[126:129], v[188:191], v[78:81], v[66:69]
	v_mfma_f32_16x16x32_bf16 v[66:69], v[192:195], v[74:77], v[122:125]
	v_mfma_f32_16x16x32_bf16 v[122:125], v[180:183], v[78:81], v[66:69]
	v_mfma_f32_16x16x32_bf16 v[66:69], v[184:187], v[216:219], v[110:113]
	v_mfma_f32_16x16x32_bf16 v[110:113], v[188:191], v[224:227], v[66:69]
	v_mfma_f32_16x16x32_bf16 v[66:69], v[192:195], v[216:219], v[106:109]
	v_mfma_f32_16x16x32_bf16 v[106:109], v[180:183], v[224:227], v[66:69]
	v_mfma_f32_16x16x32_bf16 v[66:69], v[184:187], v[228:231], v[94:97]
	v_mfma_f32_16x16x32_bf16 v[94:97], v[188:191], v[232:235], v[66:69]
	v_mfma_f32_16x16x32_bf16 v[66:69], v[192:195], v[228:231], v[90:93]
	v_mfma_f32_16x16x32_bf16 v[90:93], v[180:183], v[232:235], v[66:69]
	s_barrier
; #define PG8_SB(B) __builtin_amdgcn_rcpf(1.f + expneg(B))
; #define PG8_SB(B) __builtin_amdgcn_rcpf(1.f + expneg(B))
; #define PG8_STAGE(bufoff, gbase, voff) do { _Pragma("unroll") for (int _i = 0; _i < 2; ++_i) \
;         __builtin_amdgcn_global_load_lds((const unsigned*)((const char*)(gbase) + (size_t)_i * qstep + (voff)[0]), (PG8_LAS unsigned*)(lds + (bufoff) + ldsw + _i * 8192), 16, 0, 0); } while (0)
; #define PG8_LDA(dst, b, h) do { _Pragma("unroll") for (int m = 0; m < 4; ++m) _Pragma("unroll") for (int k = 0; k < 2; ++k) dst[m][k] = *(const PG8_LAS bf16x8*)(lds + PG8_SA(b, h) + aoff + m * 2048 + k * 1024); } while (0)
; #define PG8_MMA(ai, bj, At, Bt) do { __builtin_amdgcn_s_setprio(1); _Pragma("unroll") for (int m = 0; m < 4; ++m) _Pragma("unroll") for (int n = 0; n < 2; ++n) _Pragma("unroll") for (int k = 0; k < 2; ++k) \
;         acc[ai][bj][m][n] = __builtin_amdgcn_mfma_f32_16x16x32_bf16(Bt[n][k], At[m][k], acc[ai][bj][m][n], 0, 0, 0); __builtin_amdgcn_s_setprio(0); } while (0)
; #define PG8_WAIT_V89() do { if constexpr (SLIVER) PG8_WAIT_V(9); else PG8_WAIT_V(8); } while (0)
; #define PG8_LDS_S(b) do { if constexpr (SLIVER) { Sf[0] = *(const PG8_LAS bf16x8*)(lds + STAGE_BYTES + (b) * 2048 + soff0); Sf[1] = *(const PG8_LAS bf16x8*)(lds + STAGE_BYTES + (b) * 2048 + (soff0 ^ 64)); } } while (0)
; #define PG8_WAIT_L(n) asm volatile("s_waitcnt lgkmcnt(" #n ")" ::: "memory")
; #define PG8_BAR __builtin_amdgcn_s_barrier()
; #define PG8_SCHED __builtin_amdgcn_sched_barrier(0)
; template <class Epi, class Sched, bool ALIGN_EPI = false, bool SP2 = false, bool SLIVER = false>
; __device__ __forceinline__ void gemm_phase(PG8_LAS unsigned char* lds, const Gemm g, const Sched& S, const Epi& E) {
;     ...
;             PG8_LDA(At, 0, 1); PG8_LDS_S(0); PG8_STAGE(PG8_SB(0, 0), b2, voffB); PG8_STAGE(PG8_SB(0, 1), b2 + hstep, voffB); PG8_STAGE(PG8_SA(0, 0), a2, voffA);
;             PG8_WAIT_V89(); PG8_WAIT_L(0); PG8_BAR; PG8_MMA(1, 0, At, B0); PG8_MMA(1, 1, At, B1); PG8_MMA_S(); PG8_BAR; PG8_SCHED;
	s_setprio 0
	s_add_i32 s68, 0, 0x20000
	v_lshl_add_u64 v[216:217], s[66:67], 0, v[198:199]
	s_add_i32 s66, s69, s18
	v_add_u32_e32 v74, s68, v221
	v_add_u32_e32 v75, s68, v222
	s_mov_b32 m0, s66
	ds_read_b128 v[66:69], v223 offset:16384
	ds_read_b128 v[70:73], v223 offset:17408
	ds_read_b128 v[224:227], v223 offset:18432
	ds_read_b128 v[228:231], v223 offset:19456
	ds_read_b128 v[232:235], v223 offset:20480
	ds_read_b128 v[240:243], v223 offset:21504
	ds_read_b128 v[244:247], v223 offset:22528
	ds_read_b128 v[248:251], v223 offset:23552
	ds_read_b128 v[166:169], v74
	ds_read_b128 v[170:173], v75
	global_load_lds_dwordx4 v[216:217], off
	v_lshl_add_u64 v[74:75], v[216:217], 0, s[64:65]
	s_add_i32 m0, s66, 0x2000
	s_add_i32 s13, s13, s18
	global_load_lds_dwordx4 v[74:75], off
	v_lshl_add_u64 v[74:75], v[216:217], 0, s[0:1]
	s_mov_b32 m0, s13
	v_lshl_add_u64 v[218:219], s[40:41], 0, v[196:197]
	global_load_lds_dwordx4 v[74:75], off
	v_lshl_add_u64 v[74:75], v[216:217], 0, s[74:75]
	s_add_i32 m0, s13, 0x2000
	s_nop 0
	global_load_lds_dwordx4 v[74:75], off
	s_mov_b32 m0, s19
	v_lshl_add_u64 v[74:75], v[218:219], 0, s[64:65]
	global_load_lds_dwordx4 v[218:219], off
	s_mov_b32 m0, s52
	s_nop 0
	global_load_lds_dwordx4 v[74:75], off
	s_waitcnt vmcnt(9)
	s_waitcnt lgkmcnt(0)
	s_setprio 1
	s_barrier
	v_mfma_f32_16x16x32_bf16 v[74:77], v[154:157], v[66:69], v[86:89]
	v_mfma_f32_16x16x32_bf16 v[74:77], v[158:161], v[70:73], v[74:77]
	v_mfma_f32_16x16x32_bf16 v[78:81], v[162:165], v[66:69], v[82:85]
	v_mfma_f32_16x16x32_bf16 v[78:81], v[174:177], v[70:73], v[78:81]
	v_mfma_f32_16x16x32_bf16 v[54:57], v[154:157], v[224:227], v[54:57]
	v_mfma_f32_16x16x32_bf16 v[54:57], v[158:161], v[228:231], v[54:57]
	v_mfma_f32_16x16x32_bf16 v[50:53], v[162:165], v[224:227], v[50:53]
	v_mfma_f32_16x16x32_bf16 v[50:53], v[174:177], v[228:231], v[50:53]
	v_mfma_f32_16x16x32_bf16 v[38:41], v[154:157], v[232:235], v[38:41]
	v_mfma_f32_16x16x32_bf16 v[38:41], v[158:161], v[240:243], v[38:41]
	v_mfma_f32_16x16x32_bf16 v[34:37], v[162:165], v[232:235], v[34:37]
	v_mfma_f32_16x16x32_bf16 v[34:37], v[174:177], v[240:243], v[34:37]
	v_mfma_f32_16x16x32_bf16 v[22:25], v[154:157], v[244:247], v[22:25]
	v_mfma_f32_16x16x32_bf16 v[22:25], v[158:161], v[248:251], v[22:25]
	v_mfma_f32_16x16x32_bf16 v[18:21], v[162:165], v[244:247], v[18:21]
	v_mfma_f32_16x16x32_bf16 v[18:21], v[174:177], v[248:251], v[18:21]
	s_setprio 0
	v_mfma_f32_16x16x32_bf16 v[10:13], v[180:183], v[248:251], v[10:13]
	v_mfma_f32_16x16x32_bf16 v[10:13], v[192:195], v[244:247], v[10:13]
	s_setprio 1
	v_mfma_f32_16x16x32_bf16 v[58:61], v[192:195], v[66:69], v[58:61]
	v_mfma_f32_16x16x32_bf16 v[58:61], v[180:183], v[70:73], v[58:61]
	v_mfma_f32_16x16x32_bf16 v[62:65], v[188:191], v[70:73], v[62:65]
	v_mfma_f32_16x16x32_bf16 v[62:65], v[184:187], v[66:69], v[62:65]
	v_mfma_f32_16x16x32_bf16 v[46:49], v[184:187], v[224:227], v[46:49]
	v_mfma_f32_16x16x32_bf16 v[46:49], v[188:191], v[228:231], v[46:49]
	v_mfma_f32_16x16x32_bf16 v[42:45], v[180:183], v[228:231], v[42:45]
	v_mfma_f32_16x16x32_bf16 v[42:45], v[192:195], v[224:227], v[42:45]
	v_mfma_f32_16x16x32_bf16 v[26:29], v[192:195], v[232:235], v[26:29]
	v_mfma_f32_16x16x32_bf16 v[26:29], v[180:183], v[240:243], v[26:29]
	v_mfma_f32_16x16x32_bf16 v[30:33], v[188:191], v[240:243], v[30:33]
	v_mfma_f32_16x16x32_bf16 v[30:33], v[184:187], v[232:235], v[30:33]
	v_mfma_f32_16x16x32_bf16 v[14:17], v[184:187], v[244:247], v[14:17]
	v_mfma_f32_16x16x32_bf16 v[14:17], v[188:191], v[248:251], v[14:17]
	s_setprio 0
	s_setprio 1
	s_and_b64 vcc, exec, s[82:83]
	s_cbranch_vccz .Lslv_b2
	v_mfma_f32_16x16x32_bf16 v[66:69], v[184:187], v[166:169], v[6:9]
	v_mfma_f32_16x16x32_bf16 v[70:73], v[192:195], v[166:169], v[2:5]
	v_mfma_f32_16x16x32_bf16 v[66:69], v[188:191], v[170:173], v[66:69]
	v_mfma_f32_16x16x32_bf16 v[70:73], v[180:183], v[170:173], v[70:73]
	s_barrier
	s_setprio 0
	s_branch .Lrot_b2

; #define PG8_STAGE(bufoff, gbase, voff) do { _Pragma("unroll") for (int _i = 0; _i < 2; ++_i) \
;         __builtin_amdgcn_global_load_lds((const unsigned*)((const char*)(gbase) + (size_t)_i * qstep + (voff)[0]), (PG8_LAS unsigned*)(lds + (bufoff) + ldsw + _i * 8192), 16, 0, 0); } while (0)
; #define PG8_LDA(dst, b, h) do { _Pragma("unroll") for (int m = 0; m < 4; ++m) _Pragma("unroll") for (int k = 0; k < 2; ++k) dst[m][k] = *(const PG8_LAS bf16x8*)(lds + PG8_SA(b, h) + aoff + m * 2048 + k * 1024); } while (0)
; #define PG8_LDB(dst, b, h) do { _Pragma("unroll") for (int n = 0; n < 2; ++n) _Pragma("unroll") for (int k = 0; k < 2; ++k) dst[n][k] = *(const PG8_LAS bf16x8*)(lds + PG8_SB(b, h) + boff + n * 2048 + k * 1024); } while (0)
; #define PG8_MMA(ai, bj, At, Bt) do { __builtin_amdgcn_s_setprio(1); _Pragma("unroll") for (int m = 0; m < 4; ++m) _Pragma("unroll") for (int n = 0; n < 2; ++n) _Pragma("unroll") for (int k = 0; k < 2; ++k) \
;         acc[ai][bj][m][n] = __builtin_amdgcn_mfma_f32_16x16x32_bf16(Bt[n][k], At[m][k], acc[ai][bj][m][n], 0, 0, 0); __builtin_amdgcn_s_setprio(0); } while (0)
; #define PG8_WAIT_V89() do { if constexpr (SLIVER) PG8_WAIT_V(9); else PG8_WAIT_V(8); } while (0)
; #define PG8_STAGE_S(b, gbase) do { if constexpr (SLIVER) __builtin_amdgcn_global_load_lds((const unsigned*)((const char*)(gbase) + voffS), (PG8_LAS unsigned*)(lds + STAGE_BYTES + (b) * 2048 + wid * 256), 4, 0, 0); } while (0)
; #define PG8_WAIT_L(n) asm volatile("s_waitcnt lgkmcnt(" #n ")" ::: "memory")
; #define PG8_BAR __builtin_amdgcn_s_barrier()
; #define PG8_SCHED __builtin_amdgcn_sched_barrier(0)
; template <class Epi, class Sched, bool ALIGN_EPI = false, bool SP2 = false, bool SLIVER = false>
; __device__ __forceinline__ void gemm_phase(PG8_LAS unsigned char* lds, const Gemm g, const Sched& S, const Epi& E) {
;     ...
;             PG8_LDB(B0, 1, 0); PG8_LDB(B1, 1, 1); PG8_SCHED; PG8_LDA(At, 1, 0); PG8_STAGE(PG8_SA(0, 1), a2 + hstep, voffA); PG8_STAGE_S(0, s2);
;             PG8_WAIT_V89(); PG8_WAIT_L(0); PG8_BAR; PG8_MMA(0, 0, At, B0); PG8_MMA(0, 1, At, B1); PG8_BAR; PG8_SCHED;
.Lrot_b2:
	s_add_u32 s13, s92, s62
	s_addc_u32 s66, s93, s63
	s_add_u32 s13, s13, 0x100
	s_addc_u32 s68, s66, 0
	s_and_b64 s[66:67], s[80:81], exec
	s_cselect_b32 s67, s89, s68
	s_cselect_b32 s66, s88, s13
	s_add_i32 s13, 0, 0x18000
	v_add_u32_e32 v2, s13, v220
	s_add_i32 s68, 0, 0x1c000
	ds_read_b128 v[154:157], v2
	ds_read_b128 v[158:161], v2 offset:1024
	ds_read_b128 v[162:165], v2 offset:2048
	ds_read_b128 v[174:177], v2 offset:3072
	v_add_u32_e32 v2, s68, v220
	ds_read_b128 v[184:187], v2
	ds_read_b128 v[188:191], v2 offset:1024
	ds_read_b128 v[192:195], v2 offset:2048
	ds_read_b128 v[180:183], v2 offset:3072
	s_mov_b32 m0, s53
	v_lshl_add_u64 v[166:167], v[218:219], 0, s[0:1]
	ds_read_b128 v[2:5], v223 offset:32768
	ds_read_b128 v[6:9], v223 offset:33792
	ds_read_b128 v[82:85], v223 offset:34816
	ds_read_b128 v[86:89], v223 offset:35840
	ds_read_b128 v[224:227], v223 offset:36864
	ds_read_b128 v[228:231], v223 offset:37888
	ds_read_b128 v[232:235], v223 offset:38912
	ds_read_b128 v[240:243], v223 offset:39936
	global_load_lds_dwordx4 v[166:167], off
	v_lshl_add_u64 v[166:167], v[218:219], 0, s[74:75]
	s_mov_b32 m0, s54
	s_nop 0
	global_load_lds_dwordx4 v[166:167], off
	v_lshl_add_u64 v[166:167], s[66:67], 0, v[200:201]
	s_mov_b32 m0, s55
	s_nop 0
	global_load_lds_dword v[166:167], off
	s_waitcnt vmcnt(9)
	s_waitcnt lgkmcnt(0)
	s_setprio 1
	s_barrier
	v_mfma_f32_16x16x32_bf16 v[146:149], v[154:157], v[2:5], v[146:149]
	v_mfma_f32_16x16x32_bf16 v[170:173], v[158:161], v[6:9], v[146:149]
	v_mfma_f32_16x16x32_bf16 v[146:149], v[162:165], v[2:5], v[150:153]
	v_mfma_f32_16x16x32_bf16 v[166:169], v[174:177], v[6:9], v[146:149]
	v_mfma_f32_16x16x32_bf16 v[134:137], v[154:157], v[82:85], v[134:137]
	v_mfma_f32_16x16x32_bf16 v[134:137], v[158:161], v[86:89], v[134:137]
	v_mfma_f32_16x16x32_bf16 v[130:133], v[162:165], v[82:85], v[130:133]
	v_mfma_f32_16x16x32_bf16 v[130:133], v[174:177], v[86:89], v[130:133]
	v_mfma_f32_16x16x32_bf16 v[118:121], v[154:157], v[224:227], v[118:121]
	v_mfma_f32_16x16x32_bf16 v[118:121], v[158:161], v[228:231], v[118:121]
	v_mfma_f32_16x16x32_bf16 v[114:117], v[162:165], v[224:227], v[114:117]
	v_mfma_f32_16x16x32_bf16 v[114:117], v[174:177], v[228:231], v[114:117]
	v_mfma_f32_16x16x32_bf16 v[102:105], v[154:157], v[232:235], v[102:105]
	v_mfma_f32_16x16x32_bf16 v[102:105], v[158:161], v[240:243], v[102:105]
	v_mfma_f32_16x16x32_bf16 v[98:101], v[162:165], v[232:235], v[98:101]
	v_mfma_f32_16x16x32_bf16 v[98:101], v[174:177], v[240:243], v[98:101]
	s_setprio 0
	v_mfma_f32_16x16x32_bf16 v[142:145], v[184:187], v[2:5], v[142:145]
	v_mfma_f32_16x16x32_bf16 v[142:145], v[188:191], v[6:9], v[142:145]
	s_setprio 1
	v_mfma_f32_16x16x32_bf16 v[2:5], v[192:195], v[2:5], v[138:141]
	v_mfma_f32_16x16x32_bf16 v[138:141], v[180:183], v[6:9], v[2:5]
	v_mfma_f32_16x16x32_bf16 v[2:5], v[184:187], v[82:85], v[126:129]
	v_mfma_f32_16x16x32_bf16 v[126:129], v[188:191], v[86:89], v[2:5]
	v_mfma_f32_16x16x32_bf16 v[2:5], v[192:195], v[82:85], v[122:125]
	v_mfma_f32_16x16x32_bf16 v[122:125], v[180:183], v[86:89], v[2:5]
	v_mfma_f32_16x16x32_bf16 v[2:5], v[184:187], v[224:227], v[110:113]
	v_mfma_f32_16x16x32_bf16 v[110:113], v[188:191], v[228:231], v[2:5]
	v_mfma_f32_16x16x32_bf16 v[2:5], v[192:195], v[224:227], v[106:109]
	v_mfma_f32_16x16x32_bf16 v[106:109], v[180:183], v[228:231], v[2:5]
	v_mfma_f32_16x16x32_bf16 v[2:5], v[184:187], v[232:235], v[94:97]
	v_mfma_f32_16x16x32_bf16 v[94:97], v[188:191], v[240:243], v[2:5]
	v_mfma_f32_16x16x32_bf16 v[2:5], v[192:195], v[232:235], v[90:93]
	v_mfma_f32_16x16x32_bf16 v[90:93], v[180:183], v[240:243], v[2:5]
	s_barrier
; #define PG8_SB(B) __builtin_amdgcn_rcpf(1.f + expneg(B))
; #define PG8_SB(B) __builtin_amdgcn_rcpf(1.f + expneg(B))
; #define PG8_STAGE(bufoff, gbase, voff) do { _Pragma("unroll") for (int _i = 0; _i < 2; ++_i) \
;         __builtin_amdgcn_global_load_lds((const unsigned*)((const char*)(gbase) + (size_t)_i * qstep + (voff)[0]), (PG8_LAS unsigned*)(lds + (bufoff) + ldsw + _i * 8192), 16, 0, 0); } while (0)
; #define PG8_LDA(dst, b, h) do { _Pragma("unroll") for (int m = 0; m < 4; ++m) _Pragma("unroll") for (int k = 0; k < 2; ++k) dst[m][k] = *(const PG8_LAS bf16x8*)(lds + PG8_SA(b, h) + aoff + m * 2048 + k * 1024); } while (0)
; #define PG8_MMA(ai, bj, At, Bt) do { __builtin_amdgcn_s_setprio(1); _Pragma("unroll") for (int m = 0; m < 4; ++m) _Pragma("unroll") for (int n = 0; n < 2; ++n) _Pragma("unroll") for (int k = 0; k < 2; ++k) \
;         acc[ai][bj][m][n] = __builtin_amdgcn_mfma_f32_16x16x32_bf16(Bt[n][k], At[m][k], acc[ai][bj][m][n], 0, 0, 0); __builtin_amdgcn_s_setprio(0); } while (0)
; #define PG8_WAIT_V89() do { if constexpr (SLIVER) PG8_WAIT_V(9); else PG8_WAIT_V(8); } while (0)
; #define PG8_LDS_S(b) do { if constexpr (SLIVER) { Sf[0] = *(const PG8_LAS bf16x8*)(lds + STAGE_BYTES + (b) * 2048 + soff0); Sf[1] = *(const PG8_LAS bf16x8*)(lds + STAGE_BYTES + (b) * 2048 + (soff0 ^ 64)); } } while (0)
; #define PG8_WAIT_L(n) asm volatile("s_waitcnt lgkmcnt(" #n ")" ::: "memory")
; #define PG8_BAR __builtin_amdgcn_s_barrier()
; #define PG8_SCHED __builtin_amdgcn_sched_barrier(0)
; template <class Epi, class Sched, bool ALIGN_EPI = false, bool SP2 = false, bool SLIVER = false>
; __device__ __forceinline__ void gemm_phase(PG8_LAS unsigned char* lds, const Gemm g, const Sched& S, const Epi& E) {
;     ...
;             PG8_LDA(At, 1, 1); PG8_LDS_S(1); PG8_STAGE(PG8_SB(1, 0), b3, voffB); PG8_STAGE(PG8_SB(1, 1), b3 + hstep, voffB); PG8_STAGE(PG8_SA(1, 0), a3, voffA);
;             PG8_WAIT_V89(); PG8_WAIT_L(0); PG8_BAR; PG8_MMA(1, 0, At, B0); PG8_MMA(1, 1, At, B1); PG8_MMA_S(); PG8_BAR; PG8_SCHED;
	s_setprio 0
	s_add_i32 s66, 0, 0x20800
	v_add_u32_e32 v82, s66, v221
	v_add_u32_e32 v83, s66, v222
	s_add_i32 s13, s13, s18
	ds_read_b128 v[2:5], v223 offset:49152
	ds_read_b128 v[6:9], v223 offset:50176
	ds_read_b128 v[224:227], v223 offset:51200
	ds_read_b128 v[228:231], v223 offset:52224
	ds_read_b128 v[232:235], v223 offset:53248
	ds_read_b128 v[240:243], v223 offset:54272
	ds_read_b128 v[244:247], v223 offset:55296
	ds_read_b128 v[248:251], v223 offset:56320
	ds_read_b128 v[146:149], v82
	ds_read_b128 v[150:153], v83
	v_lshl_add_u64 v[82:83], v[216:217], 0, s[26:27]
	s_mov_b32 m0, s13
	s_mov_b64 s[66:67], 0x210080
	global_load_lds_dwordx4 v[82:83], off
	v_lshl_add_u64 v[82:83], v[216:217], 0, s[60:61]
	s_add_i32 m0, s13, 0x2000
	s_add_i32 s13, s68, s18
	global_load_lds_dwordx4 v[82:83], off
	v_lshl_add_u64 v[82:83], v[216:217], 0, s[8:9]
	s_mov_b32 m0, s13
	s_nop 0
	global_load_lds_dwordx4 v[82:83], off
	v_lshl_add_u64 v[82:83], v[216:217], 0, s[66:67]
	s_add_i32 m0, s13, 0x2000
	s_nop 0
	global_load_lds_dwordx4 v[82:83], off
	v_lshl_add_u64 v[82:83], v[218:219], 0, s[26:27]
	s_mov_b32 m0, s10
	s_nop 0
	global_load_lds_dwordx4 v[82:83], off
	v_lshl_add_u64 v[82:83], v[218:219], 0, s[60:61]
	s_mov_b32 m0, s48
	s_nop 0
	global_load_lds_dwordx4 v[82:83], off
	s_waitcnt vmcnt(9)
	s_waitcnt lgkmcnt(0)
	s_setprio 1
	s_barrier
	v_mfma_f32_16x16x32_bf16 v[74:77], v[154:157], v[2:5], v[74:77]
	v_mfma_f32_16x16x32_bf16 v[86:89], v[158:161], v[6:9], v[74:77]
	v_mfma_f32_16x16x32_bf16 v[74:77], v[162:165], v[2:5], v[78:81]
	v_mfma_f32_16x16x32_bf16 v[82:85], v[174:177], v[6:9], v[74:77]
	v_mfma_f32_16x16x32_bf16 v[54:57], v[154:157], v[224:227], v[54:57]
	v_mfma_f32_16x16x32_bf16 v[54:57], v[158:161], v[228:231], v[54:57]
	v_mfma_f32_16x16x32_bf16 v[50:53], v[162:165], v[224:227], v[50:53]
	v_mfma_f32_16x16x32_bf16 v[50:53], v[174:177], v[228:231], v[50:53]
	v_mfma_f32_16x16x32_bf16 v[38:41], v[154:157], v[232:235], v[38:41]
	v_mfma_f32_16x16x32_bf16 v[38:41], v[158:161], v[240:243], v[38:41]
	v_mfma_f32_16x16x32_bf16 v[34:37], v[162:165], v[232:235], v[34:37]
	v_mfma_f32_16x16x32_bf16 v[34:37], v[174:177], v[240:243], v[34:37]
	v_mfma_f32_16x16x32_bf16 v[22:25], v[154:157], v[244:247], v[22:25]
	v_mfma_f32_16x16x32_bf16 v[22:25], v[158:161], v[248:251], v[22:25]
	v_mfma_f32_16x16x32_bf16 v[18:21], v[162:165], v[244:247], v[18:21]
	v_mfma_f32_16x16x32_bf16 v[18:21], v[174:177], v[248:251], v[18:21]
	s_setprio 0
	v_mfma_f32_16x16x32_bf16 v[62:65], v[184:187], v[2:5], v[62:65]
	v_mfma_f32_16x16x32_bf16 v[62:65], v[188:191], v[6:9], v[62:65]
	s_setprio 1
	v_mfma_f32_16x16x32_bf16 v[2:5], v[192:195], v[2:5], v[58:61]
	v_mfma_f32_16x16x32_bf16 v[58:61], v[180:183], v[6:9], v[2:5]
	v_mfma_f32_16x16x32_bf16 v[2:5], v[184:187], v[224:227], v[46:49]
	v_mfma_f32_16x16x32_bf16 v[46:49], v[188:191], v[228:231], v[2:5]
	v_mfma_f32_16x16x32_bf16 v[2:5], v[192:195], v[224:227], v[42:45]
	v_mfma_f32_16x16x32_bf16 v[42:45], v[180:183], v[228:231], v[2:5]
	v_mfma_f32_16x16x32_bf16 v[2:5], v[184:187], v[232:235], v[30:33]
	v_mfma_f32_16x16x32_bf16 v[30:33], v[188:191], v[240:243], v[2:5]
	v_mfma_f32_16x16x32_bf16 v[2:5], v[192:195], v[232:235], v[26:29]
	v_mfma_f32_16x16x32_bf16 v[26:29], v[180:183], v[240:243], v[2:5]
	v_mfma_f32_16x16x32_bf16 v[2:5], v[184:187], v[244:247], v[14:17]
	v_mfma_f32_16x16x32_bf16 v[14:17], v[188:191], v[248:251], v[2:5]
	v_mfma_f32_16x16x32_bf16 v[2:5], v[192:195], v[244:247], v[10:13]
	v_mfma_f32_16x16x32_bf16 v[10:13], v[180:183], v[248:251], v[2:5]
	s_setprio 0
	s_setprio 1
	s_and_b64 vcc, exec, s[82:83]
	s_cbranch_vccz .Lslv_c2
	v_mfma_f32_16x16x32_bf16 v[2:5], v[184:187], v[146:149], v[66:69]
	v_mfma_f32_16x16x32_bf16 v[6:9], v[188:191], v[150:153], v[2:5]
	v_mfma_f32_16x16x32_bf16 v[2:5], v[192:195], v[146:149], v[70:73]
	v_mfma_f32_16x16x32_bf16 v[2:5], v[180:183], v[150:153], v[2:5]
	s_barrier
	s_setprio 0
	s_branch .Lrot_c2

; #define PG8_STAGE(bufoff, gbase, voff) do { _Pragma("unroll") for (int _i = 0; _i < 2; ++_i) \
;         __builtin_amdgcn_global_load_lds((const unsigned*)((const char*)(gbase) + (size_t)_i * qstep + (voff)[0]), (PG8_LAS unsigned*)(lds + (bufoff) + ldsw + _i * 8192), 16, 0, 0); } while (0)
; #define PG8_LDA(dst, b, h) do { _Pragma("unroll") for (int m = 0; m < 4; ++m) _Pragma("unroll") for (int k = 0; k < 2; ++k) dst[m][k] = *(const PG8_LAS bf16x8*)(lds + PG8_SA(b, h) + aoff + m * 2048 + k * 1024); } while (0)
; #define PG8_LDB(dst, b, h) do { _Pragma("unroll") for (int n = 0; n < 2; ++n) _Pragma("unroll") for (int k = 0; k < 2; ++k) dst[n][k] = *(const PG8_LAS bf16x8*)(lds + PG8_SB(b, h) + boff + n * 2048 + k * 1024); } while (0)
; #define PG8_MMA(ai, bj, At, Bt) do { __builtin_amdgcn_s_setprio(1); _Pragma("unroll") for (int m = 0; m < 4; ++m) _Pragma("unroll") for (int n = 0; n < 2; ++n) _Pragma("unroll") for (int k = 0; k < 2; ++k) \
;         acc[ai][bj][m][n] = __builtin_amdgcn_mfma_f32_16x16x32_bf16(Bt[n][k], At[m][k], acc[ai][bj][m][n], 0, 0, 0); __builtin_amdgcn_s_setprio(0); } while (0)
; #define PG8_WAIT_V89() do { if constexpr (SLIVER) PG8_WAIT_V(9); else PG8_WAIT_V(8); } while (0)
; #define PG8_STAGE_S(b, gbase) do { if constexpr (SLIVER) __builtin_amdgcn_global_load_lds((const unsigned*)((const char*)(gbase) + voffS), (PG8_LAS unsigned*)(lds + STAGE_BYTES + (b) * 2048 + wid * 256), 4, 0, 0); } while (0)
; #define PG8_WAIT_L(n) asm volatile("s_waitcnt lgkmcnt(" #n ")" ::: "memory")
; #define PG8_BAR __builtin_amdgcn_s_barrier()
; #define PG8_SCHED __builtin_amdgcn_sched_barrier(0)
; template <class Epi, class Sched, bool ALIGN_EPI = false, bool SP2 = false, bool SLIVER = false>
; __device__ __forceinline__ void gemm_phase(PG8_LAS unsigned char* lds, const Gemm g, const Sched& S, const Epi& E) {
;     ...
;             PG8_LDB(B0, 0, 0); PG8_LDB(B1, 0, 1); PG8_SCHED; PG8_LDA(At, 0, 0); PG8_STAGE(PG8_SA(1, 1), a1 + hstep, voffA); PG8_STAGE_S(1, s1);
;             PG8_WAIT_V89(); PG8_WAIT_L(0); PG8_BAR; PG8_MMA(0, 0, At, B0); PG8_MMA(0, 1, At, B1); PG8_BAR; PG8_SCHED;
.LBB0_934:
	s_cmp_eq_u32 s66, s62
	s_cselect_b64 s[80:81], -1, 0
	s_add_u32 s12, s42, s62
	s_addc_u32 s13, s43, s63
	s_add_u32 s40, s12, 0x100
	s_addc_u32 s41, s13, 0
	s_and_b64 s[12:13], s[80:81], exec
	s_cselect_b32 s41, s95, s41
	s_cselect_b32 s40, s94, s40
	s_add_u32 s68, s17, s62
	s_addc_u32 s69, s45, s63
	s_add_i32 s76, 0, 0x10000
	s_and_b64 s[12:13], s[80:81], exec
	v_add_u32_e32 v138, s76, v212
	s_cselect_b32 s13, s97, s69
	s_cselect_b32 s12, s96, s68
	s_add_i32 s68, 0, 0x14000
	ds_read_b128 v[146:149], v138
	ds_read_b128 v[150:153], v138 offset:1024
	ds_read_b128 v[154:157], v138 offset:2048
	ds_read_b128 v[158:161], v138 offset:3072
	v_add_u32_e32 v138, s68, v212
	ds_read_b128 v[166:169], v138
	ds_read_b128 v[170:173], v138 offset:1024
	ds_read_b128 v[174:177], v138 offset:2048
	ds_read_b128 v[162:165], v138 offset:3072
	v_lshl_add_u64 v[202:203], v[198:199], 0, s[62:63]
	s_mov_b64 vcc, 0x90080
	v_lshl_add_u64 v[208:209], v[202:203], 0, vcc
	s_add_i32 m0, s93, 0xc000
	s_mov_b64 vcc, 0xd8080
	ds_read_b128 v[138:141], v215
	ds_read_b128 v[142:145], v215 offset:1024
	ds_read_b128 v[180:183], v215 offset:2048
	ds_read_b128 v[184:187], v215 offset:3072
	ds_read_b128 v[216:219], v215 offset:4096
	ds_read_b128 v[220:223], v215 offset:5120
	ds_read_b128 v[224:227], v215 offset:6144
	ds_read_b128 v[228:231], v215 offset:7168
	global_load_lds_dwordx4 v[208:209], off
	v_lshl_add_u64 v[202:203], v[202:203], 0, vcc
	s_add_i32 m0, s93, 0xe000
	s_nop 0
	global_load_lds_dwordx4 v[202:203], off
	v_lshl_add_u64 v[202:203], v[200:201], 0, s[62:63]
	s_add_i32 m0, s50, 0x20800
	s_nop 0
	global_load_lds_dword v[202:203], off
	s_waitcnt vmcnt(9)
	s_waitcnt lgkmcnt(0)
	s_setprio 1
	s_barrier
	v_mfma_f32_16x16x32_bf16 v[134:137], v[146:149], v[138:141], v[134:137]
	v_mfma_f32_16x16x32_bf16 v[134:137], v[150:153], v[142:145], v[134:137]
	v_mfma_f32_16x16x32_bf16 v[130:133], v[158:161], v[142:145], v[130:133]
	v_mfma_f32_16x16x32_bf16 v[130:133], v[154:157], v[138:141], v[130:133]
	v_mfma_f32_16x16x32_bf16 v[122:125], v[154:157], v[180:183], v[122:125]
	v_mfma_f32_16x16x32_bf16 v[122:125], v[158:161], v[184:187], v[122:125]
	v_mfma_f32_16x16x32_bf16 v[126:129], v[150:153], v[184:187], v[126:129]
	v_mfma_f32_16x16x32_bf16 v[126:129], v[146:149], v[180:183], v[126:129]
	v_mfma_f32_16x16x32_bf16 v[114:117], v[146:149], v[216:219], v[114:117]
	v_mfma_f32_16x16x32_bf16 v[114:117], v[150:153], v[220:223], v[114:117]
	v_mfma_f32_16x16x32_bf16 v[106:109], v[158:161], v[220:223], v[106:109]
	v_mfma_f32_16x16x32_bf16 v[106:109], v[154:157], v[216:219], v[106:109]
	v_mfma_f32_16x16x32_bf16 v[90:93], v[154:157], v[224:227], v[90:93]
	v_mfma_f32_16x16x32_bf16 v[90:93], v[158:161], v[228:231], v[90:93]
	v_mfma_f32_16x16x32_bf16 v[98:101], v[150:153], v[228:231], v[98:101]
	v_mfma_f32_16x16x32_bf16 v[98:101], v[146:149], v[224:227], v[98:101]
	s_setprio 0
	v_mfma_f32_16x16x32_bf16 v[74:77], v[174:177], v[224:227], v[74:77]
	v_mfma_f32_16x16x32_bf16 v[74:77], v[162:165], v[228:231], v[74:77]
	s_setprio 1
	v_mfma_f32_16x16x32_bf16 v[110:113], v[162:165], v[142:145], v[110:113]
	v_mfma_f32_16x16x32_bf16 v[110:113], v[174:177], v[138:141], v[110:113]
	v_mfma_f32_16x16x32_bf16 v[118:121], v[166:169], v[138:141], v[118:121]
	v_mfma_f32_16x16x32_bf16 v[118:121], v[170:173], v[142:145], v[118:121]
	v_mfma_f32_16x16x32_bf16 v[102:105], v[170:173], v[184:187], v[102:105]
	v_mfma_f32_16x16x32_bf16 v[102:105], v[166:169], v[180:183], v[102:105]
	v_mfma_f32_16x16x32_bf16 v[94:97], v[174:177], v[180:183], v[94:97]
	v_mfma_f32_16x16x32_bf16 v[94:97], v[162:165], v[184:187], v[94:97]
	v_mfma_f32_16x16x32_bf16 v[82:85], v[162:165], v[220:223], v[82:85]
	v_mfma_f32_16x16x32_bf16 v[82:85], v[174:177], v[216:219], v[82:85]
	v_mfma_f32_16x16x32_bf16 v[86:89], v[166:169], v[216:219], v[86:89]
	v_mfma_f32_16x16x32_bf16 v[86:89], v[170:173], v[220:223], v[86:89]
	v_mfma_f32_16x16x32_bf16 v[78:81], v[170:173], v[228:231], v[78:81]
	v_mfma_f32_16x16x32_bf16 v[78:81], v[166:169], v[224:227], v[78:81]
	s_barrier
; #define PG8_SB(B) __builtin_amdgcn_rcpf(1.f + expneg(B))
; #define PG8_SB(B) __builtin_amdgcn_rcpf(1.f + expneg(B))
; #define PG8_STAGE(bufoff, gbase, voff) do { _Pragma("unroll") for (int _i = 0; _i < 2; ++_i) \
;         __builtin_amdgcn_global_load_lds((const unsigned*)((const char*)(gbase) + (size_t)_i * qstep + (voff)[0]), (PG8_LAS unsigned*)(lds + (bufoff) + ldsw + _i * 8192), 16, 0, 0); } while (0)
; #define PG8_LDA(dst, b, h) do { _Pragma("unroll") for (int m = 0; m < 4; ++m) _Pragma("unroll") for (int k = 0; k < 2; ++k) dst[m][k] = *(const PG8_LAS bf16x8*)(lds + PG8_SA(b, h) + aoff + m * 2048 + k * 1024); } while (0)
; #define PG8_MMA(ai, bj, At, Bt) do { __builtin_amdgcn_s_setprio(1); _Pragma("unroll") for (int m = 0; m < 4; ++m) _Pragma("unroll") for (int n = 0; n < 2; ++n) _Pragma("unroll") for (int k = 0; k < 2; ++k) \
;         acc[ai][bj][m][n] = __builtin_amdgcn_mfma_f32_16x16x32_bf16(Bt[n][k], At[m][k], acc[ai][bj][m][n], 0, 0, 0); __builtin_amdgcn_s_setprio(0); } while (0)
; #define PG8_WAIT_V89() do { if constexpr (SLIVER) PG8_WAIT_V(9); else PG8_WAIT_V(8); } while (0)
; #define PG8_LDS_S(b) do { if constexpr (SLIVER) { Sf[0] = *(const PG8_LAS bf16x8*)(lds + STAGE_BYTES + (b) * 2048 + soff0); Sf[1] = *(const PG8_LAS bf16x8*)(lds + STAGE_BYTES + (b) * 2048 + (soff0 ^ 64)); } } while (0)
; #define PG8_WAIT_L(n) asm volatile("s_waitcnt lgkmcnt(" #n ")" ::: "memory")
; #define PG8_BAR __builtin_amdgcn_s_barrier()
; #define PG8_SCHED __builtin_amdgcn_sched_barrier(0)
; template <class Epi, class Sched, bool ALIGN_EPI = false, bool SP2 = false, bool SLIVER = false>
; __device__ __forceinline__ void gemm_phase(PG8_LAS unsigned char* lds, const Gemm g, const Sched& S, const Epi& E) {
;     ...
;             PG8_LDA(At, 0, 1); PG8_LDS_S(0); PG8_STAGE(PG8_SB(0, 0), b2, voffB); PG8_STAGE(PG8_SB(0, 1), b2 + hstep, voffB); PG8_STAGE(PG8_SA(0, 0), a2, voffA);
;             PG8_WAIT_V89(); PG8_WAIT_L(0); PG8_BAR; PG8_MMA(1, 0, At, B0); PG8_MMA(1, 1, At, B1); PG8_MMA_S(); PG8_BAR; PG8_SCHED;
	s_setprio 0
	s_add_i32 s69, 0, 0x20000
	v_lshl_add_u64 v[202:203], s[12:13], 0, v[190:191]
	s_add_i32 s12, s76, s92
	v_add_u32_e32 v178, s69, v213
	v_add_u32_e32 v184, s69, v214
	s_mov_b32 m0, s12
	ds_read_b128 v[138:141], v215 offset:16384
	ds_read_b128 v[142:145], v215 offset:17408
	ds_read_b128 v[216:219], v215 offset:18432
	ds_read_b128 v[220:223], v215 offset:19456
	ds_read_b128 v[224:227], v215 offset:20480
	ds_read_b128 v[228:231], v215 offset:21504
	ds_read_b128 v[232:235], v215 offset:22528
	ds_read_b128 v[240:243], v215 offset:23552
	ds_read_b128 v[180:183], v178
	ds_read_b128 v[184:187], v184
	global_load_lds_dwordx4 v[202:203], off
	v_lshl_add_u64 v[208:209], v[202:203], 0, s[70:71]
	s_add_i32 m0, s12, 0x2000
	s_add_i32 s12, s68, s92
	global_load_lds_dwordx4 v[208:209], off
	v_lshl_add_u64 v[208:209], v[202:203], 0, s[46:47]
	s_mov_b32 m0, s12
	v_lshl_add_u64 v[210:211], s[40:41], 0, v[188:189]
	global_load_lds_dwordx4 v[208:209], off
	v_lshl_add_u64 v[208:209], v[202:203], 0, s[6:7]
	s_add_i32 m0, s12, 0x2000
	s_nop 0
	global_load_lds_dwordx4 v[208:209], off
	s_mov_b32 m0, s93
	v_lshl_add_u64 v[208:209], v[210:211], 0, s[70:71]
	global_load_lds_dwordx4 v[210:211], off
	s_mov_b32 m0, s48
	s_nop 0
	global_load_lds_dwordx4 v[208:209], off
	s_waitcnt vmcnt(9)
	s_waitcnt lgkmcnt(0)
	s_setprio 1
	s_barrier
	v_mfma_f32_16x16x32_bf16 v[70:73], v[146:149], v[138:141], v[70:73]
	v_mfma_f32_16x16x32_bf16 v[70:73], v[150:153], v[142:145], v[70:73]
	v_mfma_f32_16x16x32_bf16 v[66:69], v[158:161], v[142:145], v[66:69]
	v_mfma_f32_16x16x32_bf16 v[66:69], v[154:157], v[138:141], v[66:69]
	v_mfma_f32_16x16x32_bf16 v[58:61], v[154:157], v[216:219], v[58:61]
	v_mfma_f32_16x16x32_bf16 v[58:61], v[158:161], v[220:223], v[58:61]
	v_mfma_f32_16x16x32_bf16 v[62:65], v[150:153], v[220:223], v[62:65]
	v_mfma_f32_16x16x32_bf16 v[62:65], v[146:149], v[216:219], v[62:65]
	v_mfma_f32_16x16x32_bf16 v[50:53], v[146:149], v[224:227], v[50:53]
	v_mfma_f32_16x16x32_bf16 v[50:53], v[150:153], v[228:231], v[50:53]
	v_mfma_f32_16x16x32_bf16 v[42:45], v[158:161], v[228:231], v[42:45]
	v_mfma_f32_16x16x32_bf16 v[42:45], v[154:157], v[224:227], v[42:45]
	v_mfma_f32_16x16x32_bf16 v[26:29], v[154:157], v[232:235], v[26:29]
	v_mfma_f32_16x16x32_bf16 v[26:29], v[158:161], v[240:243], v[26:29]
	v_mfma_f32_16x16x32_bf16 v[34:37], v[150:153], v[240:243], v[34:37]
	v_mfma_f32_16x16x32_bf16 v[34:37], v[146:149], v[232:235], v[34:37]
	s_setprio 0
	v_mfma_f32_16x16x32_bf16 v[10:13], v[174:177], v[232:235], v[10:13]
	v_mfma_f32_16x16x32_bf16 v[10:13], v[162:165], v[240:243], v[10:13]
	s_setprio 1
	v_mfma_f32_16x16x32_bf16 v[46:49], v[162:165], v[142:145], v[46:49]
	v_mfma_f32_16x16x32_bf16 v[46:49], v[174:177], v[138:141], v[46:49]
	v_mfma_f32_16x16x32_bf16 v[54:57], v[166:169], v[138:141], v[54:57]
	v_mfma_f32_16x16x32_bf16 v[54:57], v[170:173], v[142:145], v[54:57]
	v_mfma_f32_16x16x32_bf16 v[38:41], v[170:173], v[220:223], v[38:41]
	v_mfma_f32_16x16x32_bf16 v[38:41], v[166:169], v[216:219], v[38:41]
	v_mfma_f32_16x16x32_bf16 v[30:33], v[174:177], v[216:219], v[30:33]
	v_mfma_f32_16x16x32_bf16 v[30:33], v[162:165], v[220:223], v[30:33]
	v_mfma_f32_16x16x32_bf16 v[18:21], v[162:165], v[228:231], v[18:21]
	v_mfma_f32_16x16x32_bf16 v[18:21], v[174:177], v[224:227], v[18:21]
	v_mfma_f32_16x16x32_bf16 v[22:25], v[166:169], v[224:227], v[22:25]
	v_mfma_f32_16x16x32_bf16 v[22:25], v[170:173], v[228:231], v[22:25]
	v_mfma_f32_16x16x32_bf16 v[14:17], v[170:173], v[240:243], v[14:17]
	v_mfma_f32_16x16x32_bf16 v[14:17], v[166:169], v[232:235], v[14:17]
	s_setprio 0
	s_setprio 1
	s_and_b64 vcc, exec, s[90:91]
	s_cbranch_vccz .Lslv_b3
	v_mfma_f32_16x16x32_bf16 v[138:141], v[166:169], v[180:183], v[6:9]
	v_mfma_f32_16x16x32_bf16 v[142:145], v[174:177], v[180:183], v[2:5]
	v_mfma_f32_16x16x32_bf16 v[138:141], v[170:173], v[184:187], v[138:141]
	v_mfma_f32_16x16x32_bf16 v[142:145], v[162:165], v[184:187], v[142:145]
	s_barrier
	s_setprio 0
	s_branch .Lrot_b3

; #define PG8_STAGE(bufoff, gbase, voff) do { _Pragma("unroll") for (int _i = 0; _i < 2; ++_i) \
;         __builtin_amdgcn_global_load_lds((const unsigned*)((const char*)(gbase) + (size_t)_i * qstep + (voff)[0]), (PG8_LAS unsigned*)(lds + (bufoff) + ldsw + _i * 8192), 16, 0, 0); } while (0)
; #define PG8_LDA(dst, b, h) do { _Pragma("unroll") for (int m = 0; m < 4; ++m) _Pragma("unroll") for (int k = 0; k < 2; ++k) dst[m][k] = *(const PG8_LAS bf16x8*)(lds + PG8_SA(b, h) + aoff + m * 2048 + k * 1024); } while (0)
; #define PG8_LDB(dst, b, h) do { _Pragma("unroll") for (int n = 0; n < 2; ++n) _Pragma("unroll") for (int k = 0; k < 2; ++k) dst[n][k] = *(const PG8_LAS bf16x8*)(lds + PG8_SB(b, h) + boff + n * 2048 + k * 1024); } while (0)
; #define PG8_MMA(ai, bj, At, Bt) do { __builtin_amdgcn_s_setprio(1); _Pragma("unroll") for (int m = 0; m < 4; ++m) _Pragma("unroll") for (int n = 0; n < 2; ++n) _Pragma("unroll") for (int k = 0; k < 2; ++k) \
;         acc[ai][bj][m][n] = __builtin_amdgcn_mfma_f32_16x16x32_bf16(Bt[n][k], At[m][k], acc[ai][bj][m][n], 0, 0, 0); __builtin_amdgcn_s_setprio(0); } while (0)
; #define PG8_WAIT_V89() do { if constexpr (SLIVER) PG8_WAIT_V(9); else PG8_WAIT_V(8); } while (0)
; #define PG8_STAGE_S(b, gbase) do { if constexpr (SLIVER) __builtin_amdgcn_global_load_lds((const unsigned*)((const char*)(gbase) + voffS), (PG8_LAS unsigned*)(lds + STAGE_BYTES + (b) * 2048 + wid * 256), 4, 0, 0); } while (0)
; #define PG8_WAIT_L(n) asm volatile("s_waitcnt lgkmcnt(" #n ")" ::: "memory")
; #define PG8_BAR __builtin_amdgcn_s_barrier()
; #define PG8_SCHED __builtin_amdgcn_sched_barrier(0)
; template <class Epi, class Sched, bool ALIGN_EPI = false, bool SP2 = false, bool SLIVER = false>
; __device__ __forceinline__ void gemm_phase(PG8_LAS unsigned char* lds, const Gemm g, const Sched& S, const Epi& E) {
;     ...
;             PG8_LDB(B0, 1, 0); PG8_LDB(B1, 1, 1); PG8_SCHED; PG8_LDA(At, 1, 0); PG8_STAGE(PG8_SA(0, 1), a2 + hstep, voffA); PG8_STAGE_S(0, s2);
;             PG8_WAIT_V89(); PG8_WAIT_L(0); PG8_BAR; PG8_MMA(0, 0, At, B0); PG8_MMA(0, 1, At, B1); PG8_BAR; PG8_SCHED;
.Lrot_b3:
	s_add_u32 s12, s54, s62
	s_addc_u32 s13, s55, s63
	s_add_u32 s68, s12, 0x100
	s_addc_u32 s69, s13, 0
	s_and_b64 s[12:13], s[80:81], exec
	s_cselect_b32 s13, s19, s69
	s_cselect_b32 s12, s18, s68
	s_add_i32 s68, 0, 0x18000
	v_add_u32_e32 v2, s68, v212
	s_add_i32 s69, 0, 0x1c000
	ds_read_b128 v[146:149], v2
	ds_read_b128 v[150:153], v2 offset:1024
	ds_read_b128 v[154:157], v2 offset:2048
	ds_read_b128 v[158:161], v2 offset:3072
	v_add_u32_e32 v2, s69, v212
	ds_read_b128 v[166:169], v2
	ds_read_b128 v[170:173], v2 offset:1024
	ds_read_b128 v[174:177], v2 offset:2048
	ds_read_b128 v[162:165], v2 offset:3072
	s_mov_b32 m0, s49
	v_lshl_add_u64 v[208:209], v[210:211], 0, s[46:47]
	ds_read_b128 v[2:5], v215 offset:32768
	ds_read_b128 v[6:9], v215 offset:33792
	ds_read_b128 v[180:183], v215 offset:34816
	ds_read_b128 v[184:187], v215 offset:35840
	ds_read_b128 v[216:219], v215 offset:36864
	ds_read_b128 v[220:223], v215 offset:37888
	ds_read_b128 v[224:227], v215 offset:38912
	ds_read_b128 v[228:231], v215 offset:39936
	global_load_lds_dwordx4 v[208:209], off
	v_lshl_add_u64 v[208:209], v[210:211], 0, s[6:7]
	s_mov_b32 m0, s88
	s_nop 0
	global_load_lds_dwordx4 v[208:209], off
	v_lshl_add_u64 v[208:209], s[12:13], 0, v[192:193]
	s_mov_b32 m0, s89
	s_nop 0
	global_load_lds_dword v[208:209], off
	s_waitcnt vmcnt(9)
	s_waitcnt lgkmcnt(0)
	s_setprio 1
	s_barrier
	v_mfma_f32_16x16x32_bf16 v[134:137], v[146:149], v[2:5], v[134:137]
	v_mfma_f32_16x16x32_bf16 v[134:137], v[150:153], v[6:9], v[134:137]
	v_mfma_f32_16x16x32_bf16 v[130:133], v[158:161], v[6:9], v[130:133]
	v_mfma_f32_16x16x32_bf16 v[130:133], v[154:157], v[2:5], v[130:133]
	v_mfma_f32_16x16x32_bf16 v[122:125], v[154:157], v[180:183], v[122:125]
	v_mfma_f32_16x16x32_bf16 v[122:125], v[158:161], v[184:187], v[122:125]
	v_mfma_f32_16x16x32_bf16 v[126:129], v[150:153], v[184:187], v[126:129]
	v_mfma_f32_16x16x32_bf16 v[126:129], v[146:149], v[180:183], v[126:129]
	v_mfma_f32_16x16x32_bf16 v[114:117], v[146:149], v[216:219], v[114:117]
	v_mfma_f32_16x16x32_bf16 v[114:117], v[150:153], v[220:223], v[114:117]
	v_mfma_f32_16x16x32_bf16 v[106:109], v[158:161], v[220:223], v[106:109]
	v_mfma_f32_16x16x32_bf16 v[106:109], v[154:157], v[216:219], v[106:109]
	v_mfma_f32_16x16x32_bf16 v[90:93], v[154:157], v[224:227], v[90:93]
	v_mfma_f32_16x16x32_bf16 v[90:93], v[158:161], v[228:231], v[90:93]
	v_mfma_f32_16x16x32_bf16 v[98:101], v[150:153], v[228:231], v[98:101]
	v_mfma_f32_16x16x32_bf16 v[98:101], v[146:149], v[224:227], v[98:101]
	s_setprio 0
	v_mfma_f32_16x16x32_bf16 v[118:121], v[166:169], v[2:5], v[118:121]
	v_mfma_f32_16x16x32_bf16 v[118:121], v[170:173], v[6:9], v[118:121]
	s_setprio 1
	v_mfma_f32_16x16x32_bf16 v[2:5], v[174:177], v[2:5], v[110:113]
	v_mfma_f32_16x16x32_bf16 v[110:113], v[162:165], v[6:9], v[2:5]
	v_mfma_f32_16x16x32_bf16 v[2:5], v[166:169], v[180:183], v[102:105]
	v_mfma_f32_16x16x32_bf16 v[102:105], v[170:173], v[184:187], v[2:5]
	v_mfma_f32_16x16x32_bf16 v[2:5], v[174:177], v[180:183], v[94:97]
	v_mfma_f32_16x16x32_bf16 v[94:97], v[162:165], v[184:187], v[2:5]
	v_mfma_f32_16x16x32_bf16 v[2:5], v[166:169], v[216:219], v[86:89]
	v_mfma_f32_16x16x32_bf16 v[86:89], v[170:173], v[220:223], v[2:5]
	v_mfma_f32_16x16x32_bf16 v[2:5], v[174:177], v[216:219], v[82:85]
	v_mfma_f32_16x16x32_bf16 v[82:85], v[162:165], v[220:223], v[2:5]
	v_mfma_f32_16x16x32_bf16 v[2:5], v[166:169], v[224:227], v[78:81]
	v_mfma_f32_16x16x32_bf16 v[78:81], v[170:173], v[228:231], v[2:5]
	v_mfma_f32_16x16x32_bf16 v[2:5], v[174:177], v[224:227], v[74:77]
	v_mfma_f32_16x16x32_bf16 v[74:77], v[162:165], v[228:231], v[2:5]
	s_barrier
; #define PG8_SB(B) __builtin_amdgcn_rcpf(1.f + expneg(B))
; #define PG8_SB(B) __builtin_amdgcn_rcpf(1.f + expneg(B))
; #define PG8_STAGE(bufoff, gbase, voff) do { _Pragma("unroll") for (int _i = 0; _i < 2; ++_i) \
;         __builtin_amdgcn_global_load_lds((const unsigned*)((const char*)(gbase) + (size_t)_i * qstep + (voff)[0]), (PG8_LAS unsigned*)(lds + (bufoff) + ldsw + _i * 8192), 16, 0, 0); } while (0)
; #define PG8_LDA(dst, b, h) do { _Pragma("unroll") for (int m = 0; m < 4; ++m) _Pragma("unroll") for (int k = 0; k < 2; ++k) dst[m][k] = *(const PG8_LAS bf16x8*)(lds + PG8_SA(b, h) + aoff + m * 2048 + k * 1024); } while (0)
; #define PG8_MMA(ai, bj, At, Bt) do { __builtin_amdgcn_s_setprio(1); _Pragma("unroll") for (int m = 0; m < 4; ++m) _Pragma("unroll") for (int n = 0; n < 2; ++n) _Pragma("unroll") for (int k = 0; k < 2; ++k) \
;         acc[ai][bj][m][n] = __builtin_amdgcn_mfma_f32_16x16x32_bf16(Bt[n][k], At[m][k], acc[ai][bj][m][n], 0, 0, 0); __builtin_amdgcn_s_setprio(0); } while (0)
; #define PG8_WAIT_V89() do { if constexpr (SLIVER) PG8_WAIT_V(9); else PG8_WAIT_V(8); } while (0)
; #define PG8_LDS_S(b) do { if constexpr (SLIVER) { Sf[0] = *(const PG8_LAS bf16x8*)(lds + STAGE_BYTES + (b) * 2048 + soff0); Sf[1] = *(const PG8_LAS bf16x8*)(lds + STAGE_BYTES + (b) * 2048 + (soff0 ^ 64)); } } while (0)
; #define PG8_WAIT_L(n) asm volatile("s_waitcnt lgkmcnt(" #n ")" ::: "memory")
; #define PG8_BAR __builtin_amdgcn_s_barrier()
; #define PG8_SCHED __builtin_amdgcn_sched_barrier(0)
; template <class Epi, class Sched, bool ALIGN_EPI = false, bool SP2 = false, bool SLIVER = false>
; __device__ __forceinline__ void gemm_phase(PG8_LAS unsigned char* lds, const Gemm g, const Sched& S, const Epi& E) {
;     ...
;             PG8_LDA(At, 1, 1); PG8_LDS_S(1); PG8_STAGE(PG8_SB(1, 0), b3, voffB); PG8_STAGE(PG8_SB(1, 1), b3 + hstep, voffB); PG8_STAGE(PG8_SA(1, 0), a3, voffA);
;             PG8_WAIT_V89(); PG8_WAIT_L(0); PG8_BAR; PG8_MMA(1, 0, At, B0); PG8_MMA(1, 1, At, B1); PG8_MMA_S(); PG8_BAR; PG8_SCHED;
	s_setprio 0
	s_add_i32 s12, 0, 0x20800
	v_add_u32_e32 v178, s12, v213
	v_add_u32_e32 v184, s12, v214
	s_add_i32 s12, s68, s92
	v_lshl_add_u64 v[208:209], v[202:203], 0, s[26:27]
	s_mov_b32 m0, s12
	ds_read_b128 v[2:5], v215 offset:49152
	ds_read_b128 v[6:9], v215 offset:50176
	ds_read_b128 v[216:219], v215 offset:51200
	ds_read_b128 v[220:223], v215 offset:52224
	ds_read_b128 v[224:227], v215 offset:53248
	ds_read_b128 v[228:231], v215 offset:54272
	ds_read_b128 v[232:235], v215 offset:55296
	ds_read_b128 v[240:243], v215 offset:56320
	ds_read_b128 v[180:183], v178
	ds_read_b128 v[184:187], v184
	global_load_lds_dwordx4 v[208:209], off
	v_lshl_add_u64 v[208:209], v[202:203], 0, s[58:59]
	s_add_i32 m0, s12, 0x2000
	s_mov_b64 s[12:13], 0x90080
	global_load_lds_dwordx4 v[208:209], off
	v_lshl_add_u64 v[208:209], v[202:203], 0, s[12:13]
	s_add_i32 s12, s69, s92
	s_mov_b32 m0, s12
	s_mov_b64 s[68:69], 0xd8080
	global_load_lds_dwordx4 v[208:209], off
	v_lshl_add_u64 v[202:203], v[202:203], 0, s[68:69]
	s_add_i32 m0, s12, 0x2000
	s_nop 0
	global_load_lds_dwordx4 v[202:203], off
	v_lshl_add_u64 v[202:203], v[210:211], 0, s[26:27]
	s_mov_b32 m0, s51
	s_nop 0
	global_load_lds_dwordx4 v[202:203], off
	v_lshl_add_u64 v[202:203], v[210:211], 0, s[58:59]
	s_mov_b32 m0, s53
	s_nop 0
	global_load_lds_dwordx4 v[202:203], off
	s_waitcnt vmcnt(9)
	s_waitcnt lgkmcnt(0)
	s_setprio 1
	s_barrier
	v_mfma_f32_16x16x32_bf16 v[70:73], v[146:149], v[2:5], v[70:73]
	v_mfma_f32_16x16x32_bf16 v[70:73], v[150:153], v[6:9], v[70:73]
	v_mfma_f32_16x16x32_bf16 v[66:69], v[158:161], v[6:9], v[66:69]
	v_mfma_f32_16x16x32_bf16 v[66:69], v[154:157], v[2:5], v[66:69]
	v_mfma_f32_16x16x32_bf16 v[58:61], v[154:157], v[216:219], v[58:61]
	v_mfma_f32_16x16x32_bf16 v[58:61], v[158:161], v[220:223], v[58:61]
	v_mfma_f32_16x16x32_bf16 v[62:65], v[150:153], v[220:223], v[62:65]
	v_mfma_f32_16x16x32_bf16 v[62:65], v[146:149], v[216:219], v[62:65]
	v_mfma_f32_16x16x32_bf16 v[50:53], v[146:149], v[224:227], v[50:53]
	v_mfma_f32_16x16x32_bf16 v[50:53], v[150:153], v[228:231], v[50:53]
	v_mfma_f32_16x16x32_bf16 v[42:45], v[158:161], v[228:231], v[42:45]
	v_mfma_f32_16x16x32_bf16 v[42:45], v[154:157], v[224:227], v[42:45]
	v_mfma_f32_16x16x32_bf16 v[26:29], v[154:157], v[232:235], v[26:29]
	v_mfma_f32_16x16x32_bf16 v[26:29], v[158:161], v[240:243], v[26:29]
	v_mfma_f32_16x16x32_bf16 v[34:37], v[150:153], v[240:243], v[34:37]
	v_mfma_f32_16x16x32_bf16 v[34:37], v[146:149], v[232:235], v[34:37]
	s_setprio 0
	v_mfma_f32_16x16x32_bf16 v[54:57], v[166:169], v[2:5], v[54:57]
	v_mfma_f32_16x16x32_bf16 v[54:57], v[170:173], v[6:9], v[54:57]
	s_setprio 1
	v_mfma_f32_16x16x32_bf16 v[2:5], v[174:177], v[2:5], v[46:49]
	v_mfma_f32_16x16x32_bf16 v[46:49], v[162:165], v[6:9], v[2:5]
	v_mfma_f32_16x16x32_bf16 v[2:5], v[166:169], v[216:219], v[38:41]
	v_mfma_f32_16x16x32_bf16 v[38:41], v[170:173], v[220:223], v[2:5]
	v_mfma_f32_16x16x32_bf16 v[2:5], v[174:177], v[216:219], v[30:33]
	v_mfma_f32_16x16x32_bf16 v[30:33], v[162:165], v[220:223], v[2:5]
	v_mfma_f32_16x16x32_bf16 v[2:5], v[166:169], v[224:227], v[22:25]
	v_mfma_f32_16x16x32_bf16 v[22:25], v[170:173], v[228:231], v[2:5]
	v_mfma_f32_16x16x32_bf16 v[2:5], v[174:177], v[224:227], v[18:21]
	v_mfma_f32_16x16x32_bf16 v[18:21], v[162:165], v[228:231], v[2:5]
	v_mfma_f32_16x16x32_bf16 v[2:5], v[166:169], v[232:235], v[14:17]
	v_mfma_f32_16x16x32_bf16 v[14:17], v[170:173], v[240:243], v[2:5]
	v_mfma_f32_16x16x32_bf16 v[2:5], v[174:177], v[232:235], v[10:13]
	v_mfma_f32_16x16x32_bf16 v[10:13], v[162:165], v[240:243], v[2:5]
	s_setprio 0
	s_setprio 1
	s_and_b64 vcc, exec, s[90:91]
	s_cbranch_vccz .Lslv_c3
	v_mfma_f32_16x16x32_bf16 v[2:5], v[166:169], v[180:183], v[138:141]
	v_mfma_f32_16x16x32_bf16 v[6:9], v[170:173], v[184:187], v[2:5]
	v_mfma_f32_16x16x32_bf16 v[2:5], v[174:177], v[180:183], v[142:145]
	v_mfma_f32_16x16x32_bf16 v[2:5], v[162:165], v[184:187], v[2:5]
	s_barrier
	s_setprio 0
	s_branch .Lrot_c3
